# march: one barrier per chunk, all LDS images double-buffered, C rows loaded coalesced into a wave-private LDS area, y rows written as whole 64-byte pieces through LDS
# speedup vs baseline: 1.0444x; 1.0101x over previous
.Lm_fwd_1:
	s_lshl_b32 s15, s7, 23
	s_lshl_b32 s96, s6, 22
	s_add_u32 s15, s15, s96
	s_lshl_b32 s96, s11, 16
	s_add_u32 s15, s15, s96
	s_add_u32 s15, s15, 0x1b000000
	s_add_u32 s38, s36, s15
	s_addc_u32 s39, s37, 0
	s_lshl_b32 s15, s8, 1
	s_add_u32 s15, s15, s5
	s_lshl_b32 s15, s15, 20
	s_lshl_b32 s96, s6, 19
	s_add_u32 s15, s15, s96
	s_lshl_b32 s96, s11, 13
	s_add_u32 s15, s15, s96
	s_add_u32 s15, s15, 0x17000000
	s_add_u32 s40, s36, s15
	s_addc_u32 s41, s37, 0
	s_lshl_b32 s15, s6, 21
	s_add_u32 s15, s15, s9
	s_lshl_b32 s96, s11, 15
	s_add_u32 s15, s15, s96
	s_add_u32 s15, s15, 0x1f000000
	s_add_u32 s42, s36, s15
	s_addc_u32 s43, s37, 0
	s_lshl_b32 s15, s6, 25
	s_lshl_b32 s96, s8, 7
	s_add_u32 s15, s15, s96
	s_lshl_b32 s96, s5, 6
	s_add_u32 s15, s15, s96
	s_lshl_b32 s96, s11, 19
	s_add_u32 s15, s15, s96
	s_lshl_b32 s96, s51, 26
	s_add_u32 s15, s15, s96
	s_add_u32 s15, s15, 0xf000000
	s_add_u32 s44, s36, s15
	s_addc_u32 s45, s37, 0
	s_add_u32 s4, s3, 1
	s_sub_i32 s5, 4, s3
	s_movk_i32 s6, 0x2200
	s_mov_b32 s7, 0xffffde00
	s_movk_i32 s8, 0x80
	s_mov_b32 s9, 0xffffff80
	s_movk_i32 s15, 0x800
	s_mov_b32 s96, 0xfffff800
	s_cmp_eq_u32 s51, 0
	s_cselect_b32 s52, s4, s5
	s_cselect_b32 s53, s7, s6
	s_cselect_b32 s54, s9, s8
	s_cselect_b32 s13, s96, s15
	s_cselect_b32 s18, 4, 7
	s_waitcnt lgkmcnt(0)
	v_mov_b32_e32 v1, s10
	v_mul_f32_e32 v1, 0x3fb8aa3b, v1
	v_exp_f32_e32 v1, v1
	s_nop 0
	v_xor_b32_e32 v1, 0x80000000, v1
	s_nop 0
	v_readfirstlane_b32 s62, v1
	v_and_b32_e32 v116, 31, v175
	v_bfe_u32 v117, v175, 5, 1
	v_bfe_u32 v118, v175, 2, 2
	v_and_b32_e32 v119, 3, v175
	v_bfe_u32 v120, v175, 4, 1
	v_and_b32_e32 v121, 63, v175
	v_lshlrev_b32_e32 v122, 5, v120
	v_lshl_add_u32 v122, v119, 3, v122
	v_lshl_add_u32 v123, v117, 3, v118
	s_cmp_lt_u32 s3, 4
	s_cbranch_scc0 .Lm_setup_hi_2
	s_lshl_b32 s4, s3, 5
	v_add_u32_e32 v128, s4, v116
	v_lshlrev_b32_e32 v129, 4, v117
	v_lshrrev_b32_e32 v124, 4, v121
	v_and_b32_e32 v125, 15, v121
	v_lshlrev_b32_e32 v125, 4, v125
	v_lshlrev_b32_e32 v126, 3, v124
	s_lshl_b32 s4, s3, 5
	v_add_u32_e32 v127, s4, v126
	v_lshl_add_u32 v164, v127, 9, v125
	v_add_u32_e32 v164, 0x100, v164
	s_mul_i32 s4, s3, 0x2200
	s_add_u32 s4, s4, 0x11000
	v_mad_u32_u24 v166, v126, s59, v125
	v_add_u32_e32 v166, s4, v166
	v_mad_u32_u24 v167, v116, s59, v129
	v_add_u32_e32 v167, s4, v167
	v_lshlrev_b32_e32 v130, 3, v117
	v_mov_b32_e32 v131, 80
	v_mad_u32_u24 v168, v116, v131, v130
	v_add_u32_e32 v168, s4, v168
	v_lshrrev_b32_e32 v124, 2, v121
	v_and_b32_e32 v125, 3, v121
	v_lshlrev_b32_e32 v125, 4, v125
	v_mad_u32_u24 v169, v124, v131, v125
	v_add_u32_e32 v169, s4, v169
	s_lshl_b32 s4, s3, 5
	v_add_u32_e32 v124, s4, v124
	v_lshl_add_u32 v170, v124, 12, v125
	v_add_u32_e32 v171, 0x10000, v170
	v_mad_u32_u24 v165, v128, s59, v129
	v_mad_u32_u24 v130, v116, s59, v129
	v_add_u32_e32 v210, 0x1e800, v130
	v_lshlrev_b32_e32 v130, 2, v128
	v_add_u32_e32 v211, 0x22c00, v130
	v_lshlrev_b32_e32 v130, 3, v117
	v_lshl_add_u32 v212, v128, 12, v130
	s_lshl_b32 s4, s3, 7
	s_add_u32 s4, s4, 0x22c00
	v_add_u32_e32 v217, s4, v129
	v_lshl_add_u32 v130, v117, 2, v118
	s_lshl_b32 s4, s3, 5
	v_add_u32_e32 v130, s4, v130
	v_mad_u32_u24 v130, v130, s60, v122
	v_add_u32_e32 v222, 0x19800, v130
	v_lshlrev_b32_e32 v129, 2, v117
	s_cmp_eq_u32 s51, 0
	s_cbranch_scc0 .Lm_mbwd_4
	v_add_u32_e32 v130, 0, v129
	v_cmp_le_u32_e64 s[64:65], v130, v116
	v_add_u32_e32 v130, 1, v129
	v_cmp_le_u32_e64 s[66:67], v130, v116
	v_add_u32_e32 v130, 2, v129
	v_cmp_le_u32_e64 s[68:69], v130, v116
	v_add_u32_e32 v130, 3, v129
	v_cmp_le_u32_e64 s[70:71], v130, v116
	v_add_u32_e32 v130, 8, v129
	v_cmp_le_u32_e64 s[72:73], v130, v116
	v_add_u32_e32 v130, 9, v129
	v_cmp_le_u32_e64 s[74:75], v130, v116
	v_add_u32_e32 v130, 10, v129
	v_cmp_le_u32_e64 s[76:77], v130, v116
	v_add_u32_e32 v130, 11, v129
	v_cmp_le_u32_e64 s[78:79], v130, v116
	v_add_u32_e32 v130, 16, v129
	v_cmp_le_u32_e64 s[80:81], v130, v116
	v_add_u32_e32 v130, 17, v129
	v_cmp_le_u32_e64 s[82:83], v130, v116
	v_add_u32_e32 v130, 18, v129
	v_cmp_le_u32_e64 s[84:85], v130, v116
	v_add_u32_e32 v130, 19, v129
	v_cmp_le_u32_e64 s[86:87], v130, v116
	v_add_u32_e32 v130, 24, v129
	v_cmp_le_u32_e64 s[88:89], v130, v116
	v_add_u32_e32 v130, 25, v129
	v_cmp_le_u32_e64 s[90:91], v130, v116
	v_add_u32_e32 v130, 26, v129
	v_cmp_le_u32_e64 s[92:93], v130, v116
	v_add_u32_e32 v130, 27, v129
	v_cmp_le_u32_e64 s[94:95], v130, v116
	s_branch .Lm_mdone_5
.Lm_mbwd_4:
	v_add_u32_e32 v130, 0, v129
	v_cmp_ge_u32_e64 s[64:65], v130, v116
	v_add_u32_e32 v130, 1, v129
	v_cmp_ge_u32_e64 s[66:67], v130, v116
	v_add_u32_e32 v130, 2, v129
	v_cmp_ge_u32_e64 s[68:69], v130, v116
	v_add_u32_e32 v130, 3, v129
	v_cmp_ge_u32_e64 s[70:71], v130, v116
	v_add_u32_e32 v130, 8, v129
	v_cmp_ge_u32_e64 s[72:73], v130, v116
	v_add_u32_e32 v130, 9, v129
	v_cmp_ge_u32_e64 s[74:75], v130, v116
	v_add_u32_e32 v130, 10, v129
	v_cmp_ge_u32_e64 s[76:77], v130, v116
	v_add_u32_e32 v130, 11, v129
	v_cmp_ge_u32_e64 s[78:79], v130, v116
	v_add_u32_e32 v130, 16, v129
	v_cmp_ge_u32_e64 s[80:81], v130, v116
	v_add_u32_e32 v130, 17, v129
	v_cmp_ge_u32_e64 s[82:83], v130, v116
	v_add_u32_e32 v130, 18, v129
	v_cmp_ge_u32_e64 s[84:85], v130, v116
	v_add_u32_e32 v130, 19, v129
	v_cmp_ge_u32_e64 s[86:87], v130, v116
	v_add_u32_e32 v130, 24, v129
	v_cmp_ge_u32_e64 s[88:89], v130, v116
	v_add_u32_e32 v130, 25, v129
	v_cmp_ge_u32_e64 s[90:91], v130, v116
	v_add_u32_e32 v130, 26, v129
	v_cmp_ge_u32_e64 s[92:93], v130, v116
	v_add_u32_e32 v130, 27, v129
	v_cmp_ge_u32_e64 s[94:95], v130, v116
.Lm_mdone_5:
	s_branch .Lm_setup_done_3
.Lm_setup_hi_2:
	v_and_b32_e32 v126, 0xff, v175
	v_lshrrev_b32_e32 v124, 4, v126
	v_and_b32_e32 v125, 15, v126
	v_lshlrev_b32_e32 v125, 4, v125
	v_lshl_add_u32 v164, v124, 12, v125
	v_lshlrev_b32_e32 v127, 3, v124
	v_mad_u32_u24 v170, v127, s59, v125
	v_lshlrev_b32_e32 v168, 4, v126
	v_add_u32_e32 v169, 0x1000, v168
	v_lshrrev_b32_e32 v126, 2, v126
	v_lshlrev_b32_e32 v127, 4, v119
	v_mad_u32_u24 v127, v126, s60, v127
	v_add_u32_e32 v171, 0x19800, v127
	v_add_u32_e32 v197, 0x1b800, v127
	v_lshlrev_b32_e32 v127, 2, v126
	v_add_u32_e32 v172, 0x22c00, v127
	v_mov_b32_e32 v173, 0x23000
	v_mad_u32_u24 v130, v123, s60, v122
	v_add_u32_e32 v192, 0x1b800, v130
	v_mad_u32_u24 v131, v123, s59, v122
	s_sub_i32 s4, s3, 4
	s_lshl_b32 s4, s4, 6
	v_add_u32_e32 v193, s4, v131
	v_add_u32_e32 v198, 0x8800, v193
	v_lshlrev_b32_e32 v130, 3, v117
	v_mad_u32_u24 v130, v116, s59, v130
	v_add_u32_e32 v130, s4, v130
	v_add_u32_e32 v194, 0x1e800, v130
	v_lshlrev_b32_e32 v195, 9, v121
	v_lshlrev_b32_e32 v130, 3, v121
	v_add_u32_e32 v196, 0x22c00, v130
	v_mov_b32_e32 v176, 0
	v_mov_b32_e32 v177, 0
	v_mov_b32_e32 v178, 0
	v_mov_b32_e32 v179, 0
	v_mov_b32_e32 v180, 0
	v_mov_b32_e32 v181, 0
	v_mov_b32_e32 v182, 0
	v_mov_b32_e32 v183, 0
	v_mov_b32_e32 v184, 0
	v_mov_b32_e32 v185, 0
	v_mov_b32_e32 v186, 0
	v_mov_b32_e32 v187, 0
	v_mov_b32_e32 v188, 0
	v_mov_b32_e32 v189, 0
	v_mov_b32_e32 v190, 0
	v_mov_b32_e32 v191, 0
.Lm_setup_done_3:
	v_lshlrev_b32_e32 v130, 4, v175
	v_add_u32_e32 v130, 0x1e800, v130
	ds_write_b128 v130, v[112:115] offset:0
	ds_write_b128 v130, v[112:115] offset:8192
	ds_write_b128 v130, v[112:115] offset:16384
	s_mov_b32 s14, 0
	s_movk_i32 s16, 1280
	s_movk_i32 s17, 2560
	s_cmp_lt_u32 s3, 4
	s_cbranch_scc0 .Lm_pro_hi_6
	global_load_dwordx4 v[4:7], v164, s[38:39] offset:0
	global_load_dwordx4 v[8:11], v164, s[38:39] offset:512
	global_load_dwordx4 v[12:15], v164, s[38:39] offset:1024
	global_load_dwordx4 v[16:19], v164, s[38:39] offset:1536
	global_load_dwordx4 v[20:23], v164, s[38:39] offset:2048
	global_load_dwordx4 v[24:27], v164, s[38:39] offset:2560
	global_load_dwordx4 v[28:31], v164, s[38:39] offset:3072
	global_load_dwordx4 v[32:35], v164, s[38:39] offset:3584
	s_add_u32 s38, s38, s46
	s_addc_u32 s39, s39, s55
	global_load_dwordx4 v[40:43], v164, s[38:39] offset:0
	global_load_dwordx4 v[44:47], v164, s[38:39] offset:512
	global_load_dwordx4 v[48:51], v164, s[38:39] offset:1024
	global_load_dwordx4 v[52:55], v164, s[38:39] offset:1536
	global_load_dwordx4 v[56:59], v164, s[38:39] offset:2048
	global_load_dwordx4 v[60:63], v164, s[38:39] offset:2560
	global_load_dwordx4 v[64:67], v164, s[38:39] offset:3072
	global_load_dwordx4 v[68:71], v164, s[38:39] offset:3584
	s_add_u32 s38, s38, s46
	s_addc_u32 s39, s39, s55
	s_waitcnt vmcnt(8)
	ds_write_b128 v166, v[4:7] offset:0
	ds_write_b128 v166, v[8:11] offset:272
	ds_write_b128 v166, v[12:15] offset:544
	ds_write_b128 v166, v[16:19] offset:816
	ds_write_b128 v166, v[20:23] offset:1088
	ds_write_b128 v166, v[24:27] offset:1360
	ds_write_b128 v166, v[28:31] offset:1632
	ds_write_b128 v166, v[32:35] offset:1904
	global_load_dwordx4 v[4:7], v164, s[38:39] offset:0
	global_load_dwordx4 v[8:11], v164, s[38:39] offset:512
	global_load_dwordx4 v[12:15], v164, s[38:39] offset:1024
	global_load_dwordx4 v[16:19], v164, s[38:39] offset:1536
	global_load_dwordx4 v[20:23], v164, s[38:39] offset:2048
	global_load_dwordx4 v[24:27], v164, s[38:39] offset:2560
	global_load_dwordx4 v[28:31], v164, s[38:39] offset:3072
	global_load_dwordx4 v[32:35], v164, s[38:39] offset:3584
	s_add_u32 s38, s38, s46
	s_addc_u32 s39, s39, s55
	s_waitcnt vmcnt(0)
	s_waitcnt lgkmcnt(0)
	s_barrier
	s_waitcnt lgkmcnt(0)
	s_barrier
	s_branch .Lm_pro_j_7
.Lm_pro_hi_6:
	s_cmp_eq_u32 s3, s18
	s_cbranch_scc0 .Lm_w7a_8
	global_load_dword v204, v195, s[42:43]
	global_load_dword v205, v195, s[42:43] offset:256
	s_add_u32 s42, s42, s48
	s_addc_u32 s43, s43, s55
.Lm_w7a_8:
	global_load_dwordx4 v[4:7], v164, s[38:39] offset:0
	global_load_dwordx4 v[8:11], v164, s[38:39] offset:512
	global_load_dwordx4 v[12:15], v164, s[38:39] offset:1024
	global_load_dwordx4 v[16:19], v164, s[38:39] offset:1536
	global_load_dwordx4 v[20:23], v164, s[38:39] offset:2048
	global_load_dwordx4 v[24:27], v164, s[38:39] offset:2560
	global_load_dwordx4 v[28:31], v164, s[38:39] offset:3072
	global_load_dwordx4 v[32:35], v164, s[38:39] offset:3584
	global_load_dwordx4 v[36:39], v168, s[40:41]
	global_load_dwordx4 v[40:43], v169, s[40:41]
	s_add_u32 s38, s38, s46
	s_addc_u32 s39, s39, s55
	s_add_u32 s40, s40, s47
	s_addc_u32 s41, s41, s55
	global_load_dwordx4 v[44:47], v164, s[38:39] offset:0
	global_load_dwordx4 v[48:51], v164, s[38:39] offset:512
	global_load_dwordx4 v[52:55], v164, s[38:39] offset:1024
	global_load_dwordx4 v[56:59], v164, s[38:39] offset:1536
	global_load_dwordx4 v[60:63], v164, s[38:39] offset:2048
	global_load_dwordx4 v[64:67], v164, s[38:39] offset:2560
	global_load_dwordx4 v[68:71], v164, s[38:39] offset:3072
	global_load_dwordx4 v[72:75], v164, s[38:39] offset:3584
	global_load_dwordx4 v[76:79], v168, s[40:41]
	global_load_dwordx4 v[80:83], v169, s[40:41]
	s_add_u32 s38, s38, s46
	s_addc_u32 s39, s39, s55
	s_add_u32 s40, s40, s47
	s_addc_u32 s41, s41, s55
	s_cmp_eq_u32 s3, s18
	s_cbranch_scc0 .Lm_w7b_9
	s_waitcnt vmcnt(20)
	v_mul_f32_e32 v116, s62, v204
	v_mul_f32_e32 v117, s62, v205
	v_add_f32_e32 v118, v116, v117
	v_add_u32_e32 v124, s14, v196
	v_add_u32_e32 v125, s14, v173
	v_add_f32_dpp v118, v118, v118 row_shr:1 row_mask:0xf bank_mask:0xf bound_ctrl:0
	s_nop 1
	v_add_f32_dpp v118, v118, v118 row_shr:2 row_mask:0xf bank_mask:0xf bound_ctrl:0
	s_nop 1
	v_add_f32_dpp v118, v118, v118 row_shr:4 row_mask:0xf bank_mask:0xf bound_ctrl:0
	s_nop 1
	v_add_f32_dpp v118, v118, v118 row_shr:8 row_mask:0xf bank_mask:0xf bound_ctrl:0
	s_nop 1
	v_add_f32_dpp v118, v118, v118 row_bcast:15 row_mask:0xa bank_mask:0xf
	s_nop 1
	v_add_f32_dpp v118, v118, v118 row_bcast:31 row_mask:0xc bank_mask:0xf
	s_nop 1
	v_readlane_b32 s97, v118, 63
	v_sub_f32_e32 v122, v118, v117
	v_mov_b32_e32 v123, v118
	s_nop 1
	s_cmp_eq_u32 s51, 0
	s_cbranch_scc1 .Lm_scanf_11
	v_sub_f32_e32 v122, s97, v122
	v_sub_f32_e32 v123, s97, v123
	v_fma_f32 v122, v204, s62, v122
	v_fma_f32 v123, v205, s62, v123
.Lm_scanf_11:
	v_mov_b32_e32 v119, s97
	v_mul_f32_e32 v122, 0x3fb8aa3b, v122
	v_mul_f32_e32 v123, 0x3fb8aa3b, v123
	v_mul_f32_e32 v119, 0x3fb8aa3b, v119
	ds_write_b64 v124, v[122:123]
	ds_write_b64 v124, v[204:205] offset:512
	ds_write_b32 v125, v119
	s_waitcnt lgkmcnt(0)
	global_load_dword v204, v195, s[42:43]
	global_load_dword v205, v195, s[42:43] offset:256
	s_add_u32 s42, s42, s48
	s_addc_u32 s43, s43, s55
.Lm_w7b_9:
	s_waitcnt lgkmcnt(0)
	s_barrier
	s_cmp_eq_u32 s3, s18
	s_cbranch_scc1 .Lm_w7c_10
	s_waitcnt vmcnt(10)
	v_add_u32_e32 v154, s14, v172
	v_add_u32_e32 v155, s14, v173
	ds_read_b32 v116, v155
	ds_read_b32 v117, v154
	ds_read_b32 v118, v154 offset:512
	ds_read_b32 v152, v154 offset:256
	ds_read_b32 v153, v154 offset:768
	ds_write_b128 v170, v[4:7] offset:0
	ds_write_b128 v170, v[8:11] offset:272
	ds_write_b128 v170, v[12:15] offset:544
	ds_write_b128 v170, v[16:19] offset:816
	ds_write_b128 v170, v[20:23] offset:1088
	ds_write_b128 v170, v[24:27] offset:1360
	ds_write_b128 v170, v[28:31] offset:1632
	ds_write_b128 v170, v[32:35] offset:1904
	v_lshlrev_b32_e32 v120, 16, v36
	v_and_b32_e32 v121, 0xffff0000, v36
	v_lshlrev_b32_e32 v122, 16, v37
	v_and_b32_e32 v123, 0xffff0000, v37
	v_lshlrev_b32_e32 v124, 16, v38
	v_and_b32_e32 v125, 0xffff0000, v38
	v_lshlrev_b32_e32 v126, 16, v39
	v_and_b32_e32 v127, 0xffff0000, v39
	s_waitcnt lgkmcnt(8)
	v_sub_f32_e32 v119, v116, v117
	v_exp_f32_e32 v119, v119
	v_mul_f32_e32 v128, v118, v120
	v_mul_f32_e32 v129, v118, v121
	v_mul_f32_e32 v130, v118, v122
	v_mul_f32_e32 v131, v118, v123
	v_mul_f32_e32 v132, v118, v124
	v_mul_f32_e32 v133, v118, v125
	v_mul_f32_e32 v134, v118, v126
	v_mul_f32_e32 v135, v118, v127
	v_mul_f32_e32 v119, v118, v119
	v_cvt_pk_bf16_f32 v144, v128, v129
	v_cvt_pk_bf16_f32 v145, v130, v131
	v_cvt_pk_bf16_f32 v146, v132, v133
	v_cvt_pk_bf16_f32 v147, v134, v135
	v_mul_f32_e32 v136, v119, v120
	v_mul_f32_e32 v137, v119, v121
	v_mul_f32_e32 v138, v119, v122
	v_mul_f32_e32 v139, v119, v123
	v_mul_f32_e32 v140, v119, v124
	v_mul_f32_e32 v141, v119, v125
	v_mul_f32_e32 v142, v119, v126
	v_mul_f32_e32 v143, v119, v127
	v_cvt_pk_bf16_f32 v148, v136, v137
	v_cvt_pk_bf16_f32 v149, v138, v139
	v_cvt_pk_bf16_f32 v150, v140, v141
	v_cvt_pk_bf16_f32 v151, v142, v143
	ds_write_b128 v171, v[144:147] offset:0
	ds_write_b128 v197, v[148:151] offset:0
	v_lshlrev_b32_e32 v120, 16, v40
	v_and_b32_e32 v121, 0xffff0000, v40
	v_lshlrev_b32_e32 v122, 16, v41
	v_and_b32_e32 v123, 0xffff0000, v41
	v_lshlrev_b32_e32 v124, 16, v42
	v_and_b32_e32 v125, 0xffff0000, v42
	v_lshlrev_b32_e32 v126, 16, v43
	v_and_b32_e32 v127, 0xffff0000, v43
	v_sub_f32_e32 v119, v116, v152
	v_exp_f32_e32 v119, v119
	v_mul_f32_e32 v128, v153, v120
	v_mul_f32_e32 v129, v153, v121
	v_mul_f32_e32 v130, v153, v122
	v_mul_f32_e32 v131, v153, v123
	v_mul_f32_e32 v132, v153, v124
	v_mul_f32_e32 v133, v153, v125
	v_mul_f32_e32 v134, v153, v126
	v_mul_f32_e32 v135, v153, v127
	v_mul_f32_e32 v119, v153, v119
	v_cvt_pk_bf16_f32 v144, v128, v129
	v_cvt_pk_bf16_f32 v145, v130, v131
	v_cvt_pk_bf16_f32 v146, v132, v133
	v_cvt_pk_bf16_f32 v147, v134, v135
	v_mul_f32_e32 v136, v119, v120
	v_mul_f32_e32 v137, v119, v121
	v_mul_f32_e32 v138, v119, v122
	v_mul_f32_e32 v139, v119, v123
	v_mul_f32_e32 v140, v119, v124
	v_mul_f32_e32 v141, v119, v125
	v_mul_f32_e32 v142, v119, v126
	v_mul_f32_e32 v143, v119, v127
	v_cvt_pk_bf16_f32 v148, v136, v137
	v_cvt_pk_bf16_f32 v149, v138, v139
	v_cvt_pk_bf16_f32 v150, v140, v141
	v_cvt_pk_bf16_f32 v151, v142, v143
	ds_write_b128 v171, v[144:147] offset:4096
	ds_write_b128 v197, v[148:151] offset:4096
	global_load_dwordx4 v[4:7], v164, s[38:39] offset:0
	global_load_dwordx4 v[8:11], v164, s[38:39] offset:512
	global_load_dwordx4 v[12:15], v164, s[38:39] offset:1024
	global_load_dwordx4 v[16:19], v164, s[38:39] offset:1536
	global_load_dwordx4 v[20:23], v164, s[38:39] offset:2048
	global_load_dwordx4 v[24:27], v164, s[38:39] offset:2560
	global_load_dwordx4 v[28:31], v164, s[38:39] offset:3072
	global_load_dwordx4 v[32:35], v164, s[38:39] offset:3584
	global_load_dwordx4 v[36:39], v168, s[40:41]
	global_load_dwordx4 v[40:43], v169, s[40:41]
	s_add_u32 s38, s38, s46
	s_addc_u32 s39, s39, s55
	s_add_u32 s40, s40, s47
	s_addc_u32 s41, s41, s55
	s_waitcnt lgkmcnt(0)
	s_barrier
	s_branch .Lm_pro_j_7
.Lm_w7c_10:
	s_waitcnt vmcnt(12)
	v_add_u32_e32 v154, s14, v172
	v_add_u32_e32 v155, s14, v173
	ds_read_b32 v116, v155
	ds_read_b32 v117, v154
	ds_read_b32 v118, v154 offset:512
	ds_read_b32 v152, v154 offset:256
	ds_read_b32 v153, v154 offset:768
	ds_write_b128 v170, v[4:7] offset:0
	ds_write_b128 v170, v[8:11] offset:272
	ds_write_b128 v170, v[12:15] offset:544
	ds_write_b128 v170, v[16:19] offset:816
	ds_write_b128 v170, v[20:23] offset:1088
	ds_write_b128 v170, v[24:27] offset:1360
	ds_write_b128 v170, v[28:31] offset:1632
	ds_write_b128 v170, v[32:35] offset:1904
	v_lshlrev_b32_e32 v120, 16, v36
	v_and_b32_e32 v121, 0xffff0000, v36
	v_lshlrev_b32_e32 v122, 16, v37
	v_and_b32_e32 v123, 0xffff0000, v37
	v_lshlrev_b32_e32 v124, 16, v38
	v_and_b32_e32 v125, 0xffff0000, v38
	v_lshlrev_b32_e32 v126, 16, v39
	v_and_b32_e32 v127, 0xffff0000, v39
	s_waitcnt lgkmcnt(8)
	v_sub_f32_e32 v119, v116, v117
	v_exp_f32_e32 v119, v119
	v_mul_f32_e32 v128, v118, v120
	v_mul_f32_e32 v129, v118, v121
	v_mul_f32_e32 v130, v118, v122
	v_mul_f32_e32 v131, v118, v123
	v_mul_f32_e32 v132, v118, v124
	v_mul_f32_e32 v133, v118, v125
	v_mul_f32_e32 v134, v118, v126
	v_mul_f32_e32 v135, v118, v127
	v_mul_f32_e32 v119, v118, v119
	v_cvt_pk_bf16_f32 v144, v128, v129
	v_cvt_pk_bf16_f32 v145, v130, v131
	v_cvt_pk_bf16_f32 v146, v132, v133
	v_cvt_pk_bf16_f32 v147, v134, v135
	v_mul_f32_e32 v136, v119, v120
	v_mul_f32_e32 v137, v119, v121
	v_mul_f32_e32 v138, v119, v122
	v_mul_f32_e32 v139, v119, v123
	v_mul_f32_e32 v140, v119, v124
	v_mul_f32_e32 v141, v119, v125
	v_mul_f32_e32 v142, v119, v126
	v_mul_f32_e32 v143, v119, v127
	v_cvt_pk_bf16_f32 v148, v136, v137
	v_cvt_pk_bf16_f32 v149, v138, v139
	v_cvt_pk_bf16_f32 v150, v140, v141
	v_cvt_pk_bf16_f32 v151, v142, v143
	ds_write_b128 v171, v[144:147] offset:0
	ds_write_b128 v197, v[148:151] offset:0
	v_lshlrev_b32_e32 v120, 16, v40
	v_and_b32_e32 v121, 0xffff0000, v40
	v_lshlrev_b32_e32 v122, 16, v41
	v_and_b32_e32 v123, 0xffff0000, v41
	v_lshlrev_b32_e32 v124, 16, v42
	v_and_b32_e32 v125, 0xffff0000, v42
	v_lshlrev_b32_e32 v126, 16, v43
	v_and_b32_e32 v127, 0xffff0000, v43
	v_sub_f32_e32 v119, v116, v152
	v_exp_f32_e32 v119, v119
	v_mul_f32_e32 v128, v153, v120
	v_mul_f32_e32 v129, v153, v121
	v_mul_f32_e32 v130, v153, v122
	v_mul_f32_e32 v131, v153, v123
	v_mul_f32_e32 v132, v153, v124
	v_mul_f32_e32 v133, v153, v125
	v_mul_f32_e32 v134, v153, v126
	v_mul_f32_e32 v135, v153, v127
	v_mul_f32_e32 v119, v153, v119
	v_cvt_pk_bf16_f32 v144, v128, v129
	v_cvt_pk_bf16_f32 v145, v130, v131
	v_cvt_pk_bf16_f32 v146, v132, v133
	v_cvt_pk_bf16_f32 v147, v134, v135
	v_mul_f32_e32 v136, v119, v120
	v_mul_f32_e32 v137, v119, v121
	v_mul_f32_e32 v138, v119, v122
	v_mul_f32_e32 v139, v119, v123
	v_mul_f32_e32 v140, v119, v124
	v_mul_f32_e32 v141, v119, v125
	v_mul_f32_e32 v142, v119, v126
	v_mul_f32_e32 v143, v119, v127
	v_cvt_pk_bf16_f32 v148, v136, v137
	v_cvt_pk_bf16_f32 v149, v138, v139
	v_cvt_pk_bf16_f32 v150, v140, v141
	v_cvt_pk_bf16_f32 v151, v142, v143
	ds_write_b128 v171, v[144:147] offset:4096
	ds_write_b128 v197, v[148:151] offset:4096
	global_load_dwordx4 v[4:7], v164, s[38:39] offset:0
	global_load_dwordx4 v[8:11], v164, s[38:39] offset:512
	global_load_dwordx4 v[12:15], v164, s[38:39] offset:1024
	global_load_dwordx4 v[16:19], v164, s[38:39] offset:1536
	global_load_dwordx4 v[20:23], v164, s[38:39] offset:2048
	global_load_dwordx4 v[24:27], v164, s[38:39] offset:2560
	global_load_dwordx4 v[28:31], v164, s[38:39] offset:3072
	global_load_dwordx4 v[32:35], v164, s[38:39] offset:3584
	global_load_dwordx4 v[36:39], v168, s[40:41]
	global_load_dwordx4 v[40:43], v169, s[40:41]
	s_add_u32 s38, s38, s46
	s_addc_u32 s39, s39, s55
	s_add_u32 s40, s40, s47
	s_addc_u32 s41, s41, s55
	s_waitcnt vmcnt(10)
	v_mul_f32_e32 v116, s62, v204
	v_mul_f32_e32 v117, s62, v205
	v_add_f32_e32 v118, v116, v117
	v_add_u32_e32 v124, s16, v196
	v_add_u32_e32 v125, s16, v173
	v_add_f32_dpp v118, v118, v118 row_shr:1 row_mask:0xf bank_mask:0xf bound_ctrl:0
	s_nop 1
	v_add_f32_dpp v118, v118, v118 row_shr:2 row_mask:0xf bank_mask:0xf bound_ctrl:0
	s_nop 1
	v_add_f32_dpp v118, v118, v118 row_shr:4 row_mask:0xf bank_mask:0xf bound_ctrl:0
	s_nop 1
	v_add_f32_dpp v118, v118, v118 row_shr:8 row_mask:0xf bank_mask:0xf bound_ctrl:0
	s_nop 1
	v_add_f32_dpp v118, v118, v118 row_bcast:15 row_mask:0xa bank_mask:0xf
	s_nop 1
	v_add_f32_dpp v118, v118, v118 row_bcast:31 row_mask:0xc bank_mask:0xf
	s_nop 1
	v_readlane_b32 s97, v118, 63
	v_sub_f32_e32 v122, v118, v117
	v_mov_b32_e32 v123, v118
	s_nop 1
	s_cmp_eq_u32 s51, 0
	s_cbranch_scc1 .Lm_scanf_12
	v_sub_f32_e32 v122, s97, v122
	v_sub_f32_e32 v123, s97, v123
	v_fma_f32 v122, v204, s62, v122
	v_fma_f32 v123, v205, s62, v123
.Lm_scanf_12:
	v_mov_b32_e32 v119, s97
	v_mul_f32_e32 v122, 0x3fb8aa3b, v122
	v_mul_f32_e32 v123, 0x3fb8aa3b, v123
	v_mul_f32_e32 v119, 0x3fb8aa3b, v119
	ds_write_b64 v124, v[122:123]
	ds_write_b64 v124, v[204:205] offset:512
	ds_write_b32 v125, v119
	s_waitcnt lgkmcnt(0)
	global_load_dword v204, v195, s[42:43]
	global_load_dword v205, v195, s[42:43] offset:256
	s_add_u32 s42, s42, s48
	s_addc_u32 s43, s43, s55
	s_waitcnt lgkmcnt(0)
	s_barrier
.Lm_pro_j_7:
	s_mov_b32 s50, 0
.Lm_loop:
	s_cmp_lt_u32 s3, 4
	s_cbranch_scc0 .Lm_hi_13
	v_mov_b32_e32 v223, v165
	v_add_u32_e32 v224, s14, v217
	v_mov_b32_e32 v225, v222
	v_add_u32_e32 v1, s14, v211
	ds_read_b128 v[176:179], v167 offset:0
	ds_read_b128 v[180:183], v167 offset:32
	ds_read_b128 v[184:187], v167 offset:64
	ds_read_b128 v[188:191], v167 offset:96
	ds_read_b128 v[192:195], v167 offset:128
	ds_read_b128 v[196:199], v167 offset:160
	ds_read_b128 v[200:203], v167 offset:192
	ds_read_b128 v[204:207], v167 offset:224
	ds_read_b128 v[148:151], v223 offset:0
	ds_read_b128 v[152:155], v223 offset:32
	ds_read_b128 v[156:159], v223 offset:64
	ds_read_b128 v[160:163], v223 offset:96
	s_waitcnt lgkmcnt(11)
	s_waitcnt lgkmcnt(3)
	v_mfma_f32_32x32x16_bf16 v[116:131], v[148:151], v[176:179], 0
	ds_read_b128 v[148:151], v223 offset:128
	s_waitcnt lgkmcnt(3)
	v_mfma_f32_32x32x16_bf16 v[116:131], v[152:155], v[180:183], v[116:131]
	ds_read_b128 v[152:155], v223 offset:160
	s_waitcnt lgkmcnt(3)
	v_mfma_f32_32x32x16_bf16 v[116:131], v[156:159], v[184:187], v[116:131]
	ds_read_b128 v[156:159], v223 offset:192
	s_waitcnt lgkmcnt(3)
	v_mfma_f32_32x32x16_bf16 v[116:131], v[160:163], v[188:191], v[116:131]
	ds_read_b128 v[160:163], v223 offset:224
	ds_read_b128 v[234:237], v224 offset:0
	ds_read_b128 v[238:241], v224 offset:32
	ds_read_b128 v[242:245], v224 offset:64
	ds_read_b128 v[246:249], v224 offset:96
	ds_read_b32 v250, v1
	s_waitcnt lgkmcnt(8)
	v_mfma_f32_32x32x16_bf16 v[116:131], v[148:151], v[192:195], v[116:131]
	s_waitcnt lgkmcnt(7)
	v_mfma_f32_32x32x16_bf16 v[116:131], v[152:155], v[196:199], v[116:131]
	s_waitcnt lgkmcnt(6)
	v_mfma_f32_32x32x16_bf16 v[116:131], v[156:159], v[200:203], v[116:131]
	s_waitcnt lgkmcnt(5)
	v_mfma_f32_32x32x16_bf16 v[116:131], v[160:163], v[204:207], v[116:131]
	s_cmp_eq_u32 s52, 1
	s_cbranch_scc1 .Lm_yfin1_18
	ds_read_b64_tr_b16 v[36:37], v225 offset:0
	ds_read_b64_tr_b16 v[38:39], v225 offset:512
	ds_read_b64_tr_b16 v[72:73], v225 offset:1024
	ds_read_b64_tr_b16 v[74:75], v225 offset:1536
	v_add_u32_e32 v223, s53, v223
	v_add_u32_e32 v224, s54, v224
	v_add_u32_e32 v225, s13, v225
	ds_read_b128 v[148:151], v223 offset:0
	ds_read_b128 v[152:155], v223 offset:32
	ds_read_b128 v[156:159], v223 offset:64
	ds_read_b128 v[160:163], v223 offset:96
	s_waitcnt lgkmcnt(9)
	s_waitcnt lgkmcnt(8)
	s_waitcnt lgkmcnt(3)
	v_mfma_f32_32x32x16_bf16 v[132:147], v[148:151], v[176:179], 0
	ds_read_b128 v[148:151], v223 offset:128
	v_sub_f32_e32 v234, v250, v234
	v_sub_f32_e32 v235, v250, v235
	v_sub_f32_e32 v236, v250, v236
	v_sub_f32_e32 v237, v250, v237
	v_sub_f32_e32 v238, v250, v238
	v_sub_f32_e32 v239, v250, v239
	v_sub_f32_e32 v240, v250, v240
	v_sub_f32_e32 v241, v250, v241
	v_sub_f32_e32 v242, v250, v242
	s_waitcnt lgkmcnt(3)
	v_mfma_f32_32x32x16_bf16 v[132:147], v[152:155], v[180:183], v[132:147]
	ds_read_b128 v[152:155], v223 offset:160
	v_sub_f32_e32 v243, v250, v243
	v_sub_f32_e32 v244, v250, v244
	v_sub_f32_e32 v245, v250, v245
	v_sub_f32_e32 v246, v250, v246
	v_sub_f32_e32 v247, v250, v247
	v_sub_f32_e32 v248, v250, v248
	v_sub_f32_e32 v249, v250, v249
	v_exp_f32_e32 v234, v234
	v_exp_f32_e32 v235, v235
	s_waitcnt lgkmcnt(3)
	v_mfma_f32_32x32x16_bf16 v[132:147], v[156:159], v[184:187], v[132:147]
	ds_read_b128 v[156:159], v223 offset:192
	v_exp_f32_e32 v236, v236
	v_exp_f32_e32 v237, v237
	v_exp_f32_e32 v238, v238
	v_exp_f32_e32 v239, v239
	v_exp_f32_e32 v240, v240
	v_exp_f32_e32 v241, v241
	v_exp_f32_e32 v242, v242
	v_exp_f32_e32 v243, v243
	v_exp_f32_e32 v244, v244
	s_waitcnt lgkmcnt(3)
	v_mfma_f32_32x32x16_bf16 v[132:147], v[160:163], v[188:191], v[132:147]
	ds_read_b128 v[160:163], v223 offset:224
	v_exp_f32_e32 v245, v245
	v_exp_f32_e32 v246, v246
	v_exp_f32_e32 v247, v247
	v_exp_f32_e32 v248, v248
	v_exp_f32_e32 v249, v249
	v_mul_f32_e32 v116, v116, v234
	v_mul_f32_e32 v117, v117, v235
	v_mul_f32_e32 v118, v118, v236
	v_mul_f32_e32 v119, v119, v237
	s_waitcnt lgkmcnt(3)
	v_mfma_f32_32x32x16_bf16 v[132:147], v[148:151], v[192:195], v[132:147]
	v_mul_f32_e32 v120, v120, v238
	v_mul_f32_e32 v121, v121, v239
	v_mul_f32_e32 v122, v122, v240
	v_mul_f32_e32 v123, v123, v241
	v_mul_f32_e32 v124, v124, v242
	v_mul_f32_e32 v125, v125, v243
	v_mul_f32_e32 v126, v126, v244
	v_mul_f32_e32 v127, v127, v245
	v_mul_f32_e32 v128, v128, v246
	s_waitcnt lgkmcnt(2)
	v_mfma_f32_32x32x16_bf16 v[132:147], v[152:155], v[196:199], v[132:147]
	v_mul_f32_e32 v129, v129, v247
	v_mul_f32_e32 v130, v130, v248
	v_mul_f32_e32 v131, v131, v249
	v_cndmask_b32_e64 v116, 0, v116, s[64:65]
	v_cndmask_b32_e64 v117, 0, v117, s[66:67]
	v_cndmask_b32_e64 v118, 0, v118, s[68:69]
	v_cndmask_b32_e64 v119, 0, v119, s[70:71]
	v_cndmask_b32_e64 v120, 0, v120, s[72:73]
	v_cndmask_b32_e64 v121, 0, v121, s[74:75]
	s_waitcnt lgkmcnt(1)
	v_mfma_f32_32x32x16_bf16 v[132:147], v[156:159], v[200:203], v[132:147]
	v_cndmask_b32_e64 v122, 0, v122, s[76:77]
	v_cndmask_b32_e64 v123, 0, v123, s[78:79]
	v_cndmask_b32_e64 v124, 0, v124, s[80:81]
	v_cndmask_b32_e64 v125, 0, v125, s[82:83]
	v_cndmask_b32_e64 v126, 0, v126, s[84:85]
	v_cndmask_b32_e64 v127, 0, v127, s[86:87]
	v_cndmask_b32_e64 v128, 0, v128, s[88:89]
	v_cndmask_b32_e64 v129, 0, v129, s[90:91]
	v_cndmask_b32_e64 v130, 0, v130, s[92:93]
	s_waitcnt lgkmcnt(0)
	v_mfma_f32_32x32x16_bf16 v[132:147], v[160:163], v[204:207], v[132:147]
	v_cndmask_b32_e64 v131, 0, v131, s[94:95]
	v_cvt_pk_bf16_f32 v116, v116, v117
	v_cvt_pk_bf16_f32 v117, v118, v119
	v_cvt_pk_bf16_f32 v118, v120, v121
	v_cvt_pk_bf16_f32 v119, v122, v123
	v_cvt_pk_bf16_f32 v120, v124, v125
	v_cvt_pk_bf16_f32 v121, v126, v127
	v_cvt_pk_bf16_f32 v122, v128, v129
	v_cvt_pk_bf16_f32 v123, v130, v131
	ds_read_b128 v[234:237], v224 offset:0
	ds_read_b128 v[238:241], v224 offset:32
	ds_read_b128 v[242:245], v224 offset:64
	ds_read_b128 v[246:249], v224 offset:96
	v_mfma_f32_32x32x16_bf16 v[76:91], v[36:39], v[116:119], 0
	v_mfma_f32_32x32x16_bf16 v[76:91], v[72:75], v[120:123], v[76:91]
	s_cmp_eq_u32 s52, 2
	s_cbranch_scc1 .Lm_yfin2_19
	ds_read_b64_tr_b16 v[36:37], v225 offset:0
	ds_read_b64_tr_b16 v[38:39], v225 offset:512
	ds_read_b64_tr_b16 v[72:73], v225 offset:1024
	ds_read_b64_tr_b16 v[74:75], v225 offset:1536
	v_add_u32_e32 v223, s53, v223
	v_add_u32_e32 v224, s54, v224
	v_add_u32_e32 v225, s13, v225
	ds_read_b128 v[148:151], v223 offset:0
	ds_read_b128 v[152:155], v223 offset:32
	ds_read_b128 v[156:159], v223 offset:64
	ds_read_b128 v[160:163], v223 offset:96
	s_waitcnt lgkmcnt(8)
	s_waitcnt lgkmcnt(3)
	v_mfma_f32_32x32x16_bf16 v[116:131], v[148:151], v[176:179], 0
	ds_read_b128 v[148:151], v223 offset:128
	v_sub_f32_e32 v234, v250, v234
	v_sub_f32_e32 v235, v250, v235
	v_sub_f32_e32 v236, v250, v236
	v_sub_f32_e32 v237, v250, v237
	v_sub_f32_e32 v238, v250, v238
	v_sub_f32_e32 v239, v250, v239
	v_sub_f32_e32 v240, v250, v240
	s_waitcnt lgkmcnt(3)
	v_mfma_f32_32x32x16_bf16 v[116:131], v[152:155], v[180:183], v[116:131]
	ds_read_b128 v[152:155], v223 offset:160
	v_sub_f32_e32 v241, v250, v241
	v_sub_f32_e32 v242, v250, v242
	v_sub_f32_e32 v243, v250, v243
	v_sub_f32_e32 v244, v250, v244
	v_sub_f32_e32 v245, v250, v245
	v_sub_f32_e32 v246, v250, v246
	v_sub_f32_e32 v247, v250, v247
	s_waitcnt lgkmcnt(3)
	v_mfma_f32_32x32x16_bf16 v[116:131], v[156:159], v[184:187], v[116:131]
	ds_read_b128 v[156:159], v223 offset:192
	v_sub_f32_e32 v248, v250, v248
	v_sub_f32_e32 v249, v250, v249
	v_exp_f32_e32 v234, v234
	v_exp_f32_e32 v235, v235
	v_exp_f32_e32 v236, v236
	v_exp_f32_e32 v237, v237
	v_exp_f32_e32 v238, v238
	s_waitcnt lgkmcnt(3)
	v_mfma_f32_32x32x16_bf16 v[116:131], v[160:163], v[188:191], v[116:131]
	ds_read_b128 v[160:163], v223 offset:224
	v_exp_f32_e32 v239, v239
	v_exp_f32_e32 v240, v240
	v_exp_f32_e32 v241, v241
	v_exp_f32_e32 v242, v242
	v_exp_f32_e32 v243, v243
	v_exp_f32_e32 v244, v244
	v_exp_f32_e32 v245, v245
	s_waitcnt lgkmcnt(3)
	v_mfma_f32_32x32x16_bf16 v[116:131], v[148:151], v[192:195], v[116:131]
	v_exp_f32_e32 v246, v246
	v_exp_f32_e32 v247, v247
	v_exp_f32_e32 v248, v248
	v_exp_f32_e32 v249, v249
	v_mul_f32_e32 v132, v132, v234
	v_mul_f32_e32 v133, v133, v235
	v_mul_f32_e32 v134, v134, v236
	s_waitcnt lgkmcnt(2)
	v_mfma_f32_32x32x16_bf16 v[116:131], v[152:155], v[196:199], v[116:131]
	v_mul_f32_e32 v135, v135, v237
	v_mul_f32_e32 v136, v136, v238
	v_mul_f32_e32 v137, v137, v239
	v_mul_f32_e32 v138, v138, v240
	v_mul_f32_e32 v139, v139, v241
	v_mul_f32_e32 v140, v140, v242
	v_mul_f32_e32 v141, v141, v243
	s_waitcnt lgkmcnt(1)
	v_mfma_f32_32x32x16_bf16 v[116:131], v[156:159], v[200:203], v[116:131]
	v_mul_f32_e32 v142, v142, v244
	v_mul_f32_e32 v143, v143, v245
	v_mul_f32_e32 v144, v144, v246
	v_mul_f32_e32 v145, v145, v247
	v_mul_f32_e32 v146, v146, v248
	v_mul_f32_e32 v147, v147, v249
	v_cvt_pk_bf16_f32 v132, v132, v133
	s_waitcnt lgkmcnt(0)
	v_mfma_f32_32x32x16_bf16 v[116:131], v[160:163], v[204:207], v[116:131]
	v_cvt_pk_bf16_f32 v133, v134, v135
	v_cvt_pk_bf16_f32 v134, v136, v137
	v_cvt_pk_bf16_f32 v135, v138, v139
	v_cvt_pk_bf16_f32 v136, v140, v141
	v_cvt_pk_bf16_f32 v137, v142, v143
	v_cvt_pk_bf16_f32 v138, v144, v145
	v_cvt_pk_bf16_f32 v139, v146, v147
	ds_read_b128 v[234:237], v224 offset:0
	ds_read_b128 v[238:241], v224 offset:32
	ds_read_b128 v[242:245], v224 offset:64
	ds_read_b128 v[246:249], v224 offset:96
	v_mfma_f32_32x32x16_bf16 v[76:91], v[36:39], v[132:135], v[76:91]
	v_mfma_f32_32x32x16_bf16 v[76:91], v[72:75], v[136:139], v[76:91]
	s_cmp_eq_u32 s52, 3
	s_cbranch_scc1 .Lm_yfin3_20
	ds_read_b64_tr_b16 v[36:37], v225 offset:0
	ds_read_b64_tr_b16 v[38:39], v225 offset:512
	ds_read_b64_tr_b16 v[72:73], v225 offset:1024
	ds_read_b64_tr_b16 v[74:75], v225 offset:1536
	v_add_u32_e32 v223, s53, v223
	v_add_u32_e32 v224, s54, v224
	v_add_u32_e32 v225, s13, v225
	ds_read_b128 v[148:151], v223 offset:0
	ds_read_b128 v[152:155], v223 offset:32
	ds_read_b128 v[156:159], v223 offset:64
	ds_read_b128 v[160:163], v223 offset:96
	s_waitcnt lgkmcnt(8)
	s_waitcnt lgkmcnt(3)
	v_mfma_f32_32x32x16_bf16 v[132:147], v[148:151], v[176:179], 0
	ds_read_b128 v[148:151], v223 offset:128
	v_sub_f32_e32 v234, v250, v234
	v_sub_f32_e32 v235, v250, v235
	v_sub_f32_e32 v236, v250, v236
	v_sub_f32_e32 v237, v250, v237
	v_sub_f32_e32 v238, v250, v238
	v_sub_f32_e32 v239, v250, v239
	v_sub_f32_e32 v240, v250, v240
	s_waitcnt lgkmcnt(3)
	v_mfma_f32_32x32x16_bf16 v[132:147], v[152:155], v[180:183], v[132:147]
	ds_read_b128 v[152:155], v223 offset:160
	v_sub_f32_e32 v241, v250, v241
	v_sub_f32_e32 v242, v250, v242
	v_sub_f32_e32 v243, v250, v243
	v_sub_f32_e32 v244, v250, v244
	v_sub_f32_e32 v245, v250, v245
	v_sub_f32_e32 v246, v250, v246
	v_sub_f32_e32 v247, v250, v247
	s_waitcnt lgkmcnt(3)
	v_mfma_f32_32x32x16_bf16 v[132:147], v[156:159], v[184:187], v[132:147]
	ds_read_b128 v[156:159], v223 offset:192
	v_sub_f32_e32 v248, v250, v248
	v_sub_f32_e32 v249, v250, v249
	v_exp_f32_e32 v234, v234
	v_exp_f32_e32 v235, v235
	v_exp_f32_e32 v236, v236
	v_exp_f32_e32 v237, v237
	v_exp_f32_e32 v238, v238
	s_waitcnt lgkmcnt(3)
	v_mfma_f32_32x32x16_bf16 v[132:147], v[160:163], v[188:191], v[132:147]
	ds_read_b128 v[160:163], v223 offset:224
	v_exp_f32_e32 v239, v239
	v_exp_f32_e32 v240, v240
	v_exp_f32_e32 v241, v241
	v_exp_f32_e32 v242, v242
	v_exp_f32_e32 v243, v243
	v_exp_f32_e32 v244, v244
	v_exp_f32_e32 v245, v245
	s_waitcnt lgkmcnt(3)
	v_mfma_f32_32x32x16_bf16 v[132:147], v[148:151], v[192:195], v[132:147]
	v_exp_f32_e32 v246, v246
	v_exp_f32_e32 v247, v247
	v_exp_f32_e32 v248, v248
	v_exp_f32_e32 v249, v249
	v_mul_f32_e32 v116, v116, v234
	v_mul_f32_e32 v117, v117, v235
	v_mul_f32_e32 v118, v118, v236
	s_waitcnt lgkmcnt(2)
	v_mfma_f32_32x32x16_bf16 v[132:147], v[152:155], v[196:199], v[132:147]
	v_mul_f32_e32 v119, v119, v237
	v_mul_f32_e32 v120, v120, v238
	v_mul_f32_e32 v121, v121, v239
	v_mul_f32_e32 v122, v122, v240
	v_mul_f32_e32 v123, v123, v241
	v_mul_f32_e32 v124, v124, v242
	v_mul_f32_e32 v125, v125, v243
	s_waitcnt lgkmcnt(1)
	v_mfma_f32_32x32x16_bf16 v[132:147], v[156:159], v[200:203], v[132:147]
	v_mul_f32_e32 v126, v126, v244
	v_mul_f32_e32 v127, v127, v245
	v_mul_f32_e32 v128, v128, v246
	v_mul_f32_e32 v129, v129, v247
	v_mul_f32_e32 v130, v130, v248
	v_mul_f32_e32 v131, v131, v249
	v_cvt_pk_bf16_f32 v116, v116, v117
	s_waitcnt lgkmcnt(0)
	v_mfma_f32_32x32x16_bf16 v[132:147], v[160:163], v[204:207], v[132:147]
	v_cvt_pk_bf16_f32 v117, v118, v119
	v_cvt_pk_bf16_f32 v118, v120, v121
	v_cvt_pk_bf16_f32 v119, v122, v123
	v_cvt_pk_bf16_f32 v120, v124, v125
	v_cvt_pk_bf16_f32 v121, v126, v127
	v_cvt_pk_bf16_f32 v122, v128, v129
	v_cvt_pk_bf16_f32 v123, v130, v131
	ds_read_b128 v[234:237], v224 offset:0
	ds_read_b128 v[238:241], v224 offset:32
	ds_read_b128 v[242:245], v224 offset:64
	ds_read_b128 v[246:249], v224 offset:96
	v_mfma_f32_32x32x16_bf16 v[76:91], v[36:39], v[116:119], v[76:91]
	v_mfma_f32_32x32x16_bf16 v[76:91], v[72:75], v[120:123], v[76:91]
	ds_read_b64_tr_b16 v[36:37], v225 offset:0
	ds_read_b64_tr_b16 v[38:39], v225 offset:512
	ds_read_b64_tr_b16 v[72:73], v225 offset:1024
	ds_read_b64_tr_b16 v[74:75], v225 offset:1536
	s_waitcnt lgkmcnt(4)
	ds_read_b128 v[148:151], v210 offset:0
	ds_read_b128 v[152:155], v210 offset:32
	ds_read_b128 v[156:159], v210 offset:64
	ds_read_b128 v[160:163], v210 offset:96
	s_waitcnt lgkmcnt(3)
	v_mfma_f32_32x32x16_bf16 v[92:107], v[148:151], v[176:179], 0
	ds_read_b128 v[148:151], v210 offset:128
	v_sub_f32_e32 v234, v250, v234
	v_sub_f32_e32 v235, v250, v235
	v_sub_f32_e32 v236, v250, v236
	v_sub_f32_e32 v237, v250, v237
	v_sub_f32_e32 v238, v250, v238
	v_sub_f32_e32 v239, v250, v239
	v_sub_f32_e32 v240, v250, v240
	s_waitcnt lgkmcnt(3)
	v_mfma_f32_32x32x16_bf16 v[92:107], v[152:155], v[180:183], v[92:107]
	ds_read_b128 v[152:155], v210 offset:160
	v_sub_f32_e32 v241, v250, v241
	v_sub_f32_e32 v242, v250, v242
	v_sub_f32_e32 v243, v250, v243
	v_sub_f32_e32 v244, v250, v244
	v_sub_f32_e32 v245, v250, v245
	v_sub_f32_e32 v246, v250, v246
	v_sub_f32_e32 v247, v250, v247
	s_waitcnt lgkmcnt(3)
	v_mfma_f32_32x32x16_bf16 v[92:107], v[156:159], v[184:187], v[92:107]
	ds_read_b128 v[156:159], v210 offset:192
	v_sub_f32_e32 v248, v250, v248
	v_sub_f32_e32 v249, v250, v249
	v_exp_f32_e32 v234, v234
	v_exp_f32_e32 v235, v235
	v_exp_f32_e32 v236, v236
	v_exp_f32_e32 v237, v237
	v_exp_f32_e32 v238, v238
	s_waitcnt lgkmcnt(3)
	v_mfma_f32_32x32x16_bf16 v[92:107], v[160:163], v[188:191], v[92:107]
	ds_read_b128 v[160:163], v210 offset:224
	v_exp_f32_e32 v239, v239
	v_exp_f32_e32 v240, v240
	v_exp_f32_e32 v241, v241
	v_exp_f32_e32 v242, v242
	v_exp_f32_e32 v243, v243
	v_exp_f32_e32 v244, v244
	v_exp_f32_e32 v245, v245
	s_waitcnt lgkmcnt(3)
	v_mfma_f32_32x32x16_bf16 v[92:107], v[148:151], v[192:195], v[92:107]
	v_exp_f32_e32 v246, v246
	v_exp_f32_e32 v247, v247
	v_exp_f32_e32 v248, v248
	v_exp_f32_e32 v249, v249
	v_mul_f32_e32 v132, v132, v234
	v_mul_f32_e32 v133, v133, v235
	v_mul_f32_e32 v134, v134, v236
	s_waitcnt lgkmcnt(2)
	v_mfma_f32_32x32x16_bf16 v[92:107], v[152:155], v[196:199], v[92:107]
	v_mul_f32_e32 v135, v135, v237
	v_mul_f32_e32 v136, v136, v238
	v_mul_f32_e32 v137, v137, v239
	v_mul_f32_e32 v138, v138, v240
	v_mul_f32_e32 v139, v139, v241
	v_mul_f32_e32 v140, v140, v242
	v_mul_f32_e32 v141, v141, v243
	s_waitcnt lgkmcnt(1)
	v_mfma_f32_32x32x16_bf16 v[92:107], v[156:159], v[200:203], v[92:107]
	v_mul_f32_e32 v142, v142, v244
	v_mul_f32_e32 v143, v143, v245
	v_mul_f32_e32 v144, v144, v246
	v_mul_f32_e32 v145, v145, v247
	v_mul_f32_e32 v146, v146, v248
	v_mul_f32_e32 v147, v147, v249
	v_cvt_pk_bf16_f32 v132, v132, v133
	s_waitcnt lgkmcnt(0)
	v_mfma_f32_32x32x16_bf16 v[92:107], v[160:163], v[204:207], v[92:107]
	v_cvt_pk_bf16_f32 v133, v134, v135
	v_cvt_pk_bf16_f32 v134, v136, v137
	v_cvt_pk_bf16_f32 v135, v138, v139
	v_cvt_pk_bf16_f32 v136, v140, v141
	v_cvt_pk_bf16_f32 v137, v142, v143
	v_cvt_pk_bf16_f32 v138, v144, v145
	v_cvt_pk_bf16_f32 v139, v146, v147
	v_mfma_f32_32x32x16_bf16 v[76:91], v[36:39], v[132:135], v[76:91]
	v_mfma_f32_32x32x16_bf16 v[76:91], v[72:75], v[136:139], v[76:91]
	s_branch .Lm_ydone_21

.Lm_ydone_21:
	s_waitcnt lgkmcnt(0)
	v_exp_f32_e32 v250, v250
	s_nop 7
	s_nop 3
	v_fma_f32 v76, v92, v250, v76
	v_fma_f32 v77, v93, v250, v77
	v_fma_f32 v78, v94, v250, v78
	v_fma_f32 v79, v95, v250, v79
	v_fma_f32 v80, v96, v250, v80
	v_fma_f32 v81, v97, v250, v81
	v_fma_f32 v82, v98, v250, v82
	v_fma_f32 v83, v99, v250, v83
	v_fma_f32 v84, v100, v250, v84
	v_fma_f32 v85, v101, v250, v85
	v_fma_f32 v86, v102, v250, v86
	v_fma_f32 v87, v103, v250, v87
	v_fma_f32 v88, v104, v250, v88
	v_fma_f32 v89, v105, v250, v89
	v_fma_f32 v90, v106, v250, v90
	v_fma_f32 v91, v107, v250, v91
	v_cvt_pk_bf16_f32 v148, v76, v77
	v_cvt_pk_bf16_f32 v149, v78, v79
	v_cvt_pk_bf16_f32 v150, v80, v81
	v_cvt_pk_bf16_f32 v151, v82, v83
	v_cvt_pk_bf16_f32 v152, v84, v85
	v_cvt_pk_bf16_f32 v153, v86, v87
	v_cvt_pk_bf16_f32 v154, v88, v89
	v_cvt_pk_bf16_f32 v155, v90, v91
	ds_write_b64 v168, v[148:149] offset:0
	ds_write_b64 v168, v[150:151] offset:16
	ds_write_b64 v168, v[152:153] offset:32
	ds_write_b64 v168, v[154:155] offset:48
	s_waitcnt lgkmcnt(0)
	ds_read_b128 v[156:159], v169
	ds_read_b128 v[160:163], v169 offset:1280
	s_waitcnt lgkmcnt(0)
	global_store_dwordx4 v170, v[156:159], s[44:45]
	global_store_dwordx4 v171, v[160:163], s[44:45]
	s_add_u32 s44, s44, s49
	s_addc_u32 s45, s45, s55
	s_waitcnt vmcnt(12)
	ds_write_b128 v166, v[40:43] offset:0
	ds_write_b128 v166, v[44:47] offset:272
	ds_write_b128 v166, v[48:51] offset:544
	ds_write_b128 v166, v[52:55] offset:816
	ds_write_b128 v166, v[56:59] offset:1088
	ds_write_b128 v166, v[60:63] offset:1360
	ds_write_b128 v166, v[64:67] offset:1632
	ds_write_b128 v166, v[68:71] offset:1904
	global_load_dwordx4 v[40:43], v164, s[38:39] offset:0
	global_load_dwordx4 v[44:47], v164, s[38:39] offset:512
	global_load_dwordx4 v[48:51], v164, s[38:39] offset:1024
	global_load_dwordx4 v[52:55], v164, s[38:39] offset:1536
	global_load_dwordx4 v[56:59], v164, s[38:39] offset:2048
	global_load_dwordx4 v[60:63], v164, s[38:39] offset:2560
	global_load_dwordx4 v[64:67], v164, s[38:39] offset:3072
	global_load_dwordx4 v[68:71], v164, s[38:39] offset:3584
	s_add_u32 s38, s38, s46
	s_addc_u32 s39, s39, s55
	s_branch .Lm_stepdone_14
.Lm_hi_13:
	v_add_u32_e32 v2, s14, v173
	ds_read_b32 v1, v2
	ds_read_b64_tr_b16 v[116:117], v193 offset:0
	ds_read_b64_tr_b16 v[118:119], v193 offset:1088
	ds_read_b64_tr_b16 v[120:121], v192 offset:0
	ds_read_b64_tr_b16 v[122:123], v192 offset:256
	ds_read_b64_tr_b16 v[124:125], v193 offset:4352
	ds_read_b64_tr_b16 v[126:127], v193 offset:5440
	ds_read_b64_tr_b16 v[128:129], v192 offset:1024
	ds_read_b64_tr_b16 v[130:131], v192 offset:1280
	ds_read_b64_tr_b16 v[132:133], v193 offset:8704
	ds_read_b64_tr_b16 v[134:135], v193 offset:9792
	ds_read_b64_tr_b16 v[136:137], v192 offset:2048
	ds_read_b64_tr_b16 v[138:139], v192 offset:2304
	s_waitcnt lgkmcnt(12)
	v_exp_f32_e32 v1, v1
	s_nop 0
	v_mul_f32_e32 v176, v176, v1
	v_mul_f32_e32 v177, v177, v1
	v_mul_f32_e32 v178, v178, v1
	v_mul_f32_e32 v179, v179, v1
	v_mul_f32_e32 v180, v180, v1
	v_mul_f32_e32 v181, v181, v1
	v_mul_f32_e32 v182, v182, v1
	v_mul_f32_e32 v183, v183, v1
	v_mul_f32_e32 v184, v184, v1
	v_mul_f32_e32 v185, v185, v1
	v_mul_f32_e32 v186, v186, v1
	v_mul_f32_e32 v187, v187, v1
	v_mul_f32_e32 v188, v188, v1
	v_mul_f32_e32 v189, v189, v1
	v_mul_f32_e32 v190, v190, v1
	v_mul_f32_e32 v191, v191, v1
	s_nop 1
	s_waitcnt lgkmcnt(8)
	v_mfma_f32_32x32x16_bf16 v[176:191], v[116:119], v[120:123], v[176:191]
	ds_read_b64_tr_b16 v[116:117], v193 offset:13056
	ds_read_b64_tr_b16 v[118:119], v193 offset:14144
	ds_read_b64_tr_b16 v[120:121], v192 offset:3072
	ds_read_b64_tr_b16 v[122:123], v192 offset:3328
	s_waitcnt lgkmcnt(8)
	v_mfma_f32_32x32x16_bf16 v[176:191], v[124:127], v[128:131], v[176:191]
	ds_read_b64_tr_b16 v[124:125], v193 offset:17408
	ds_read_b64_tr_b16 v[126:127], v193 offset:18496
	ds_read_b64_tr_b16 v[128:129], v192 offset:4096
	ds_read_b64_tr_b16 v[130:131], v192 offset:4352
	s_waitcnt lgkmcnt(8)
	v_mfma_f32_32x32x16_bf16 v[176:191], v[132:135], v[136:139], v[176:191]
	ds_read_b64_tr_b16 v[132:133], v193 offset:21760
	ds_read_b64_tr_b16 v[134:135], v193 offset:22848
	ds_read_b64_tr_b16 v[136:137], v192 offset:5120
	ds_read_b64_tr_b16 v[138:139], v192 offset:5376
	s_waitcnt lgkmcnt(8)
	v_mfma_f32_32x32x16_bf16 v[176:191], v[116:119], v[120:123], v[176:191]
	ds_read_b64_tr_b16 v[116:117], v193 offset:26112
	ds_read_b64_tr_b16 v[118:119], v193 offset:27200
	ds_read_b64_tr_b16 v[120:121], v192 offset:6144
	ds_read_b64_tr_b16 v[122:123], v192 offset:6400
	s_waitcnt lgkmcnt(8)
	v_mfma_f32_32x32x16_bf16 v[176:191], v[124:127], v[128:131], v[176:191]
	ds_read_b64_tr_b16 v[124:125], v193 offset:30464
	ds_read_b64_tr_b16 v[126:127], v193 offset:31552
	ds_read_b64_tr_b16 v[128:129], v192 offset:7168
	ds_read_b64_tr_b16 v[130:131], v192 offset:7424
	s_waitcnt lgkmcnt(8)
	v_mfma_f32_32x32x16_bf16 v[176:191], v[132:135], v[136:139], v[176:191]
	s_waitcnt lgkmcnt(4)
	v_mfma_f32_32x32x16_bf16 v[176:191], v[116:119], v[120:123], v[176:191]
	s_waitcnt lgkmcnt(0)
	v_mfma_f32_32x32x16_bf16 v[176:191], v[124:127], v[128:131], v[176:191]
	s_nop 7
	s_nop 3
	v_cvt_pk_bf16_f32 v140, v176, v177
	v_cvt_pk_bf16_f32 v141, v178, v179
	v_cvt_pk_bf16_f32 v142, v180, v181
	v_cvt_pk_bf16_f32 v143, v182, v183
	v_cvt_pk_bf16_f32 v144, v184, v185
	v_cvt_pk_bf16_f32 v145, v186, v187
	v_cvt_pk_bf16_f32 v146, v188, v189
	v_cvt_pk_bf16_f32 v147, v190, v191
	ds_write_b64 v194, v[140:141] offset:8704
	ds_write_b64 v194, v[142:143] offset:8720
	ds_write_b64 v194, v[144:145] offset:8736
	ds_write_b64 v194, v[146:147] offset:8752
	s_cmp_eq_u32 s3, s18
	s_cbranch_scc1 .Lm_w7_16
	s_waitcnt vmcnt(10)
	s_branch .Lm_wj_17
.Lm_w7_16:
	s_waitcnt vmcnt(12)
.Lm_wj_17:
	v_add_u32_e32 v154, s16, v172
	v_add_u32_e32 v155, s16, v173
	ds_read_b32 v116, v155
	ds_read_b32 v117, v154
	ds_read_b32 v118, v154 offset:512
	ds_read_b32 v152, v154 offset:256
	ds_read_b32 v153, v154 offset:768
	ds_write_b128 v170, v[44:47] offset:34816
	ds_write_b128 v170, v[48:51] offset:35088
	ds_write_b128 v170, v[52:55] offset:35360
	ds_write_b128 v170, v[56:59] offset:35632
	ds_write_b128 v170, v[60:63] offset:35904
	ds_write_b128 v170, v[64:67] offset:36176
	ds_write_b128 v170, v[68:71] offset:36448
	ds_write_b128 v170, v[72:75] offset:36720
	v_lshlrev_b32_e32 v120, 16, v76
	v_and_b32_e32 v121, 0xffff0000, v76
	v_lshlrev_b32_e32 v122, 16, v77
	v_and_b32_e32 v123, 0xffff0000, v77
	v_lshlrev_b32_e32 v124, 16, v78
	v_and_b32_e32 v125, 0xffff0000, v78
	v_lshlrev_b32_e32 v126, 16, v79
	v_and_b32_e32 v127, 0xffff0000, v79
	s_waitcnt lgkmcnt(8)
	v_sub_f32_e32 v119, v116, v117
	v_exp_f32_e32 v119, v119
	v_mul_f32_e32 v128, v118, v120
	v_mul_f32_e32 v129, v118, v121
	v_mul_f32_e32 v130, v118, v122
	v_mul_f32_e32 v131, v118, v123
	v_mul_f32_e32 v132, v118, v124
	v_mul_f32_e32 v133, v118, v125
	v_mul_f32_e32 v134, v118, v126
	v_mul_f32_e32 v135, v118, v127
	v_mul_f32_e32 v119, v118, v119
	v_cvt_pk_bf16_f32 v144, v128, v129
	v_cvt_pk_bf16_f32 v145, v130, v131
	v_cvt_pk_bf16_f32 v146, v132, v133
	v_cvt_pk_bf16_f32 v147, v134, v135
	v_mul_f32_e32 v136, v119, v120
	v_mul_f32_e32 v137, v119, v121
	v_mul_f32_e32 v138, v119, v122
	v_mul_f32_e32 v139, v119, v123
	v_mul_f32_e32 v140, v119, v124
	v_mul_f32_e32 v141, v119, v125
	v_mul_f32_e32 v142, v119, v126
	v_mul_f32_e32 v143, v119, v127
	v_cvt_pk_bf16_f32 v148, v136, v137
	v_cvt_pk_bf16_f32 v149, v138, v139
	v_cvt_pk_bf16_f32 v150, v140, v141
	v_cvt_pk_bf16_f32 v151, v142, v143
	ds_write_b128 v171, v[144:147] offset:43008
	ds_write_b128 v197, v[148:151] offset:43008
	v_lshlrev_b32_e32 v120, 16, v80
	v_and_b32_e32 v121, 0xffff0000, v80
	v_lshlrev_b32_e32 v122, 16, v81
	v_and_b32_e32 v123, 0xffff0000, v81
	v_lshlrev_b32_e32 v124, 16, v82
	v_and_b32_e32 v125, 0xffff0000, v82
	v_lshlrev_b32_e32 v126, 16, v83
	v_and_b32_e32 v127, 0xffff0000, v83
	v_sub_f32_e32 v119, v116, v152
	v_exp_f32_e32 v119, v119
	v_mul_f32_e32 v128, v153, v120
	v_mul_f32_e32 v129, v153, v121
	v_mul_f32_e32 v130, v153, v122
	v_mul_f32_e32 v131, v153, v123
	v_mul_f32_e32 v132, v153, v124
	v_mul_f32_e32 v133, v153, v125
	v_mul_f32_e32 v134, v153, v126
	v_mul_f32_e32 v135, v153, v127
	v_mul_f32_e32 v119, v153, v119
	v_cvt_pk_bf16_f32 v144, v128, v129
	v_cvt_pk_bf16_f32 v145, v130, v131
	v_cvt_pk_bf16_f32 v146, v132, v133
	v_cvt_pk_bf16_f32 v147, v134, v135
	v_mul_f32_e32 v136, v119, v120
	v_mul_f32_e32 v137, v119, v121
	v_mul_f32_e32 v138, v119, v122
	v_mul_f32_e32 v139, v119, v123
	v_mul_f32_e32 v140, v119, v124
	v_mul_f32_e32 v141, v119, v125
	v_mul_f32_e32 v142, v119, v126
	v_mul_f32_e32 v143, v119, v127
	v_cvt_pk_bf16_f32 v148, v136, v137
	v_cvt_pk_bf16_f32 v149, v138, v139
	v_cvt_pk_bf16_f32 v150, v140, v141
	v_cvt_pk_bf16_f32 v151, v142, v143
	ds_write_b128 v171, v[144:147] offset:47104
	ds_write_b128 v197, v[148:151] offset:47104
	global_load_dwordx4 v[44:47], v164, s[38:39] offset:0
	global_load_dwordx4 v[48:51], v164, s[38:39] offset:512
	global_load_dwordx4 v[52:55], v164, s[38:39] offset:1024
	global_load_dwordx4 v[56:59], v164, s[38:39] offset:1536
	global_load_dwordx4 v[60:63], v164, s[38:39] offset:2048
	global_load_dwordx4 v[64:67], v164, s[38:39] offset:2560
	global_load_dwordx4 v[68:71], v164, s[38:39] offset:3072
	global_load_dwordx4 v[72:75], v164, s[38:39] offset:3584
	global_load_dwordx4 v[76:79], v168, s[40:41]
	global_load_dwordx4 v[80:83], v169, s[40:41]
	s_add_u32 s38, s38, s46
	s_addc_u32 s39, s39, s55
	s_add_u32 s40, s40, s47
	s_addc_u32 s41, s41, s55
	s_cmp_eq_u32 s3, s18
	s_cbranch_scc0 .Lm_noscan_15
	s_waitcnt vmcnt(10)
	v_mul_f32_e32 v116, s62, v204
	v_mul_f32_e32 v117, s62, v205
	v_add_f32_e32 v118, v116, v117
	v_add_u32_e32 v124, s17, v196
	v_add_u32_e32 v125, s17, v173
	v_add_f32_dpp v118, v118, v118 row_shr:1 row_mask:0xf bank_mask:0xf bound_ctrl:0
	s_nop 1
	v_add_f32_dpp v118, v118, v118 row_shr:2 row_mask:0xf bank_mask:0xf bound_ctrl:0
	s_nop 1
	v_add_f32_dpp v118, v118, v118 row_shr:4 row_mask:0xf bank_mask:0xf bound_ctrl:0
	s_nop 1
	v_add_f32_dpp v118, v118, v118 row_shr:8 row_mask:0xf bank_mask:0xf bound_ctrl:0
	s_nop 1
	v_add_f32_dpp v118, v118, v118 row_bcast:15 row_mask:0xa bank_mask:0xf
	s_nop 1
	v_add_f32_dpp v118, v118, v118 row_bcast:31 row_mask:0xc bank_mask:0xf
	s_nop 1
	v_readlane_b32 s97, v118, 63
	v_sub_f32_e32 v122, v118, v117
	v_mov_b32_e32 v123, v118
	s_nop 1
	s_cmp_eq_u32 s51, 0
	s_cbranch_scc1 .Lm_scanf_22
	v_sub_f32_e32 v122, s97, v122
	v_sub_f32_e32 v123, s97, v123
	v_fma_f32 v122, v204, s62, v122
	v_fma_f32 v123, v205, s62, v123

.Lm_noscan_15:
.Lm_stepdone_14:
	s_waitcnt lgkmcnt(0)
	s_barrier
	s_mov_b32 s14, s16
	s_mov_b32 s16, s17
	s_add_u32 s17, s17, 1280
	s_cmpk_eq_u32 s17, 5120
	s_cselect_b32 s17, 0, s17
	s_add_u32 s50, s50, 1
	s_cmp_lt_u32 s3, 4
	s_cbranch_scc0 .Lm_hi_23
	v_mov_b32_e32 v223, v165
	v_add_u32_e32 v224, s14, v217
	v_mov_b32_e32 v225, v222
	v_add_u32_e32 v1, s14, v211
	ds_read_b128 v[176:179], v167 offset:0
	ds_read_b128 v[180:183], v167 offset:32
	ds_read_b128 v[184:187], v167 offset:64
	ds_read_b128 v[188:191], v167 offset:96
	ds_read_b128 v[192:195], v167 offset:128
	ds_read_b128 v[196:199], v167 offset:160
	ds_read_b128 v[200:203], v167 offset:192
	ds_read_b128 v[204:207], v167 offset:224
	ds_read_b128 v[148:151], v223 offset:34816
	ds_read_b128 v[152:155], v223 offset:34848
	ds_read_b128 v[156:159], v223 offset:34880
	ds_read_b128 v[160:163], v223 offset:34912
	s_waitcnt lgkmcnt(11)
	s_waitcnt lgkmcnt(3)
	v_mfma_f32_32x32x16_bf16 v[116:131], v[148:151], v[176:179], 0
	ds_read_b128 v[148:151], v223 offset:34944
	s_waitcnt lgkmcnt(3)
	v_mfma_f32_32x32x16_bf16 v[116:131], v[152:155], v[180:183], v[116:131]
	ds_read_b128 v[152:155], v223 offset:34976
	s_waitcnt lgkmcnt(3)
	v_mfma_f32_32x32x16_bf16 v[116:131], v[156:159], v[184:187], v[116:131]
	ds_read_b128 v[156:159], v223 offset:35008
	s_waitcnt lgkmcnt(3)
	v_mfma_f32_32x32x16_bf16 v[116:131], v[160:163], v[188:191], v[116:131]
	ds_read_b128 v[160:163], v223 offset:35040
	ds_read_b128 v[234:237], v224 offset:0
	ds_read_b128 v[238:241], v224 offset:32
	ds_read_b128 v[242:245], v224 offset:64
	ds_read_b128 v[246:249], v224 offset:96
	ds_read_b32 v250, v1
	s_waitcnt lgkmcnt(8)
	v_mfma_f32_32x32x16_bf16 v[116:131], v[148:151], v[192:195], v[116:131]
	s_waitcnt lgkmcnt(7)
	v_mfma_f32_32x32x16_bf16 v[116:131], v[152:155], v[196:199], v[116:131]
	s_waitcnt lgkmcnt(6)
	v_mfma_f32_32x32x16_bf16 v[116:131], v[156:159], v[200:203], v[116:131]
	s_waitcnt lgkmcnt(5)
	v_mfma_f32_32x32x16_bf16 v[116:131], v[160:163], v[204:207], v[116:131]
	s_cmp_eq_u32 s52, 1
	s_cbranch_scc1 .Lm_yfin1_28
	ds_read_b64_tr_b16 v[36:37], v225 offset:43008
	ds_read_b64_tr_b16 v[38:39], v225 offset:43520
	ds_read_b64_tr_b16 v[72:73], v225 offset:44032
	ds_read_b64_tr_b16 v[74:75], v225 offset:44544
	v_add_u32_e32 v223, s53, v223
	v_add_u32_e32 v224, s54, v224
	v_add_u32_e32 v225, s13, v225
	ds_read_b128 v[148:151], v223 offset:34816
	ds_read_b128 v[152:155], v223 offset:34848
	ds_read_b128 v[156:159], v223 offset:34880
	ds_read_b128 v[160:163], v223 offset:34912
	s_waitcnt lgkmcnt(9)
	s_waitcnt lgkmcnt(8)
	s_waitcnt lgkmcnt(3)
	v_mfma_f32_32x32x16_bf16 v[132:147], v[148:151], v[176:179], 0
	ds_read_b128 v[148:151], v223 offset:34944
	v_sub_f32_e32 v234, v250, v234
	v_sub_f32_e32 v235, v250, v235
	v_sub_f32_e32 v236, v250, v236
	v_sub_f32_e32 v237, v250, v237
	v_sub_f32_e32 v238, v250, v238
	v_sub_f32_e32 v239, v250, v239
	v_sub_f32_e32 v240, v250, v240
	v_sub_f32_e32 v241, v250, v241
	v_sub_f32_e32 v242, v250, v242
	s_waitcnt lgkmcnt(3)
	v_mfma_f32_32x32x16_bf16 v[132:147], v[152:155], v[180:183], v[132:147]
	ds_read_b128 v[152:155], v223 offset:34976
	v_sub_f32_e32 v243, v250, v243
	v_sub_f32_e32 v244, v250, v244
	v_sub_f32_e32 v245, v250, v245
	v_sub_f32_e32 v246, v250, v246
	v_sub_f32_e32 v247, v250, v247
	v_sub_f32_e32 v248, v250, v248
	v_sub_f32_e32 v249, v250, v249
	v_exp_f32_e32 v234, v234
	v_exp_f32_e32 v235, v235
	s_waitcnt lgkmcnt(3)
	v_mfma_f32_32x32x16_bf16 v[132:147], v[156:159], v[184:187], v[132:147]
	ds_read_b128 v[156:159], v223 offset:35008
	v_exp_f32_e32 v236, v236
	v_exp_f32_e32 v237, v237
	v_exp_f32_e32 v238, v238
	v_exp_f32_e32 v239, v239
	v_exp_f32_e32 v240, v240
	v_exp_f32_e32 v241, v241
	v_exp_f32_e32 v242, v242
	v_exp_f32_e32 v243, v243
	v_exp_f32_e32 v244, v244
	s_waitcnt lgkmcnt(3)
	v_mfma_f32_32x32x16_bf16 v[132:147], v[160:163], v[188:191], v[132:147]
	ds_read_b128 v[160:163], v223 offset:35040
	v_exp_f32_e32 v245, v245
	v_exp_f32_e32 v246, v246
	v_exp_f32_e32 v247, v247
	v_exp_f32_e32 v248, v248
	v_exp_f32_e32 v249, v249
	v_mul_f32_e32 v116, v116, v234
	v_mul_f32_e32 v117, v117, v235
	v_mul_f32_e32 v118, v118, v236
	v_mul_f32_e32 v119, v119, v237
	s_waitcnt lgkmcnt(3)
	v_mfma_f32_32x32x16_bf16 v[132:147], v[148:151], v[192:195], v[132:147]
	v_mul_f32_e32 v120, v120, v238
	v_mul_f32_e32 v121, v121, v239
	v_mul_f32_e32 v122, v122, v240
	v_mul_f32_e32 v123, v123, v241
	v_mul_f32_e32 v124, v124, v242
	v_mul_f32_e32 v125, v125, v243
	v_mul_f32_e32 v126, v126, v244
	v_mul_f32_e32 v127, v127, v245
	v_mul_f32_e32 v128, v128, v246
	s_waitcnt lgkmcnt(2)
	v_mfma_f32_32x32x16_bf16 v[132:147], v[152:155], v[196:199], v[132:147]
	v_mul_f32_e32 v129, v129, v247
	v_mul_f32_e32 v130, v130, v248
	v_mul_f32_e32 v131, v131, v249
	v_cndmask_b32_e64 v116, 0, v116, s[64:65]
	v_cndmask_b32_e64 v117, 0, v117, s[66:67]
	v_cndmask_b32_e64 v118, 0, v118, s[68:69]
	v_cndmask_b32_e64 v119, 0, v119, s[70:71]
	v_cndmask_b32_e64 v120, 0, v120, s[72:73]
	v_cndmask_b32_e64 v121, 0, v121, s[74:75]
	s_waitcnt lgkmcnt(1)
	v_mfma_f32_32x32x16_bf16 v[132:147], v[156:159], v[200:203], v[132:147]
	v_cndmask_b32_e64 v122, 0, v122, s[76:77]
	v_cndmask_b32_e64 v123, 0, v123, s[78:79]
	v_cndmask_b32_e64 v124, 0, v124, s[80:81]
	v_cndmask_b32_e64 v125, 0, v125, s[82:83]
	v_cndmask_b32_e64 v126, 0, v126, s[84:85]
	v_cndmask_b32_e64 v127, 0, v127, s[86:87]
	v_cndmask_b32_e64 v128, 0, v128, s[88:89]
	v_cndmask_b32_e64 v129, 0, v129, s[90:91]
	v_cndmask_b32_e64 v130, 0, v130, s[92:93]
	s_waitcnt lgkmcnt(0)
	v_mfma_f32_32x32x16_bf16 v[132:147], v[160:163], v[204:207], v[132:147]
	v_cndmask_b32_e64 v131, 0, v131, s[94:95]
	v_cvt_pk_bf16_f32 v116, v116, v117
	v_cvt_pk_bf16_f32 v117, v118, v119
	v_cvt_pk_bf16_f32 v118, v120, v121
	v_cvt_pk_bf16_f32 v119, v122, v123
	v_cvt_pk_bf16_f32 v120, v124, v125
	v_cvt_pk_bf16_f32 v121, v126, v127
	v_cvt_pk_bf16_f32 v122, v128, v129
	v_cvt_pk_bf16_f32 v123, v130, v131
	ds_read_b128 v[234:237], v224 offset:0
	ds_read_b128 v[238:241], v224 offset:32
	ds_read_b128 v[242:245], v224 offset:64
	ds_read_b128 v[246:249], v224 offset:96
	v_mfma_f32_32x32x16_bf16 v[76:91], v[36:39], v[116:119], 0
	v_mfma_f32_32x32x16_bf16 v[76:91], v[72:75], v[120:123], v[76:91]
	s_cmp_eq_u32 s52, 2
	s_cbranch_scc1 .Lm_yfin2_29
	ds_read_b64_tr_b16 v[36:37], v225 offset:43008
	ds_read_b64_tr_b16 v[38:39], v225 offset:43520
	ds_read_b64_tr_b16 v[72:73], v225 offset:44032
	ds_read_b64_tr_b16 v[74:75], v225 offset:44544
	v_add_u32_e32 v223, s53, v223
	v_add_u32_e32 v224, s54, v224
	v_add_u32_e32 v225, s13, v225
	ds_read_b128 v[148:151], v223 offset:34816
	ds_read_b128 v[152:155], v223 offset:34848
	ds_read_b128 v[156:159], v223 offset:34880
	ds_read_b128 v[160:163], v223 offset:34912
	s_waitcnt lgkmcnt(8)
	s_waitcnt lgkmcnt(3)
	v_mfma_f32_32x32x16_bf16 v[116:131], v[148:151], v[176:179], 0
	ds_read_b128 v[148:151], v223 offset:34944
	v_sub_f32_e32 v234, v250, v234
	v_sub_f32_e32 v235, v250, v235
	v_sub_f32_e32 v236, v250, v236
	v_sub_f32_e32 v237, v250, v237
	v_sub_f32_e32 v238, v250, v238
	v_sub_f32_e32 v239, v250, v239
	v_sub_f32_e32 v240, v250, v240
	s_waitcnt lgkmcnt(3)
	v_mfma_f32_32x32x16_bf16 v[116:131], v[152:155], v[180:183], v[116:131]
	ds_read_b128 v[152:155], v223 offset:34976
	v_sub_f32_e32 v241, v250, v241
	v_sub_f32_e32 v242, v250, v242
	v_sub_f32_e32 v243, v250, v243
	v_sub_f32_e32 v244, v250, v244
	v_sub_f32_e32 v245, v250, v245
	v_sub_f32_e32 v246, v250, v246
	v_sub_f32_e32 v247, v250, v247
	s_waitcnt lgkmcnt(3)
	v_mfma_f32_32x32x16_bf16 v[116:131], v[156:159], v[184:187], v[116:131]
	ds_read_b128 v[156:159], v223 offset:35008
	v_sub_f32_e32 v248, v250, v248
	v_sub_f32_e32 v249, v250, v249
	v_exp_f32_e32 v234, v234
	v_exp_f32_e32 v235, v235
	v_exp_f32_e32 v236, v236
	v_exp_f32_e32 v237, v237
	v_exp_f32_e32 v238, v238
	s_waitcnt lgkmcnt(3)
	v_mfma_f32_32x32x16_bf16 v[116:131], v[160:163], v[188:191], v[116:131]
	ds_read_b128 v[160:163], v223 offset:35040
	v_exp_f32_e32 v239, v239
	v_exp_f32_e32 v240, v240
	v_exp_f32_e32 v241, v241
	v_exp_f32_e32 v242, v242
	v_exp_f32_e32 v243, v243
	v_exp_f32_e32 v244, v244
	v_exp_f32_e32 v245, v245
	s_waitcnt lgkmcnt(3)
	v_mfma_f32_32x32x16_bf16 v[116:131], v[148:151], v[192:195], v[116:131]
	v_exp_f32_e32 v246, v246
	v_exp_f32_e32 v247, v247
	v_exp_f32_e32 v248, v248
	v_exp_f32_e32 v249, v249
	v_mul_f32_e32 v132, v132, v234
	v_mul_f32_e32 v133, v133, v235
	v_mul_f32_e32 v134, v134, v236
	s_waitcnt lgkmcnt(2)
	v_mfma_f32_32x32x16_bf16 v[116:131], v[152:155], v[196:199], v[116:131]
	v_mul_f32_e32 v135, v135, v237
	v_mul_f32_e32 v136, v136, v238
	v_mul_f32_e32 v137, v137, v239
	v_mul_f32_e32 v138, v138, v240
	v_mul_f32_e32 v139, v139, v241
	v_mul_f32_e32 v140, v140, v242
	v_mul_f32_e32 v141, v141, v243
	s_waitcnt lgkmcnt(1)
	v_mfma_f32_32x32x16_bf16 v[116:131], v[156:159], v[200:203], v[116:131]
	v_mul_f32_e32 v142, v142, v244
	v_mul_f32_e32 v143, v143, v245
	v_mul_f32_e32 v144, v144, v246
	v_mul_f32_e32 v145, v145, v247
	v_mul_f32_e32 v146, v146, v248
	v_mul_f32_e32 v147, v147, v249
	v_cvt_pk_bf16_f32 v132, v132, v133
	s_waitcnt lgkmcnt(0)
	v_mfma_f32_32x32x16_bf16 v[116:131], v[160:163], v[204:207], v[116:131]
	v_cvt_pk_bf16_f32 v133, v134, v135
	v_cvt_pk_bf16_f32 v134, v136, v137
	v_cvt_pk_bf16_f32 v135, v138, v139
	v_cvt_pk_bf16_f32 v136, v140, v141
	v_cvt_pk_bf16_f32 v137, v142, v143
	v_cvt_pk_bf16_f32 v138, v144, v145
	v_cvt_pk_bf16_f32 v139, v146, v147
	ds_read_b128 v[234:237], v224 offset:0
	ds_read_b128 v[238:241], v224 offset:32
	ds_read_b128 v[242:245], v224 offset:64
	ds_read_b128 v[246:249], v224 offset:96
	v_mfma_f32_32x32x16_bf16 v[76:91], v[36:39], v[132:135], v[76:91]
	v_mfma_f32_32x32x16_bf16 v[76:91], v[72:75], v[136:139], v[76:91]
	s_cmp_eq_u32 s52, 3
	s_cbranch_scc1 .Lm_yfin3_30
	ds_read_b64_tr_b16 v[36:37], v225 offset:43008
	ds_read_b64_tr_b16 v[38:39], v225 offset:43520
	ds_read_b64_tr_b16 v[72:73], v225 offset:44032
	ds_read_b64_tr_b16 v[74:75], v225 offset:44544
	v_add_u32_e32 v223, s53, v223
	v_add_u32_e32 v224, s54, v224
	v_add_u32_e32 v225, s13, v225
	ds_read_b128 v[148:151], v223 offset:34816
	ds_read_b128 v[152:155], v223 offset:34848
	ds_read_b128 v[156:159], v223 offset:34880
	ds_read_b128 v[160:163], v223 offset:34912
	s_waitcnt lgkmcnt(8)
	s_waitcnt lgkmcnt(3)
	v_mfma_f32_32x32x16_bf16 v[132:147], v[148:151], v[176:179], 0
	ds_read_b128 v[148:151], v223 offset:34944
	v_sub_f32_e32 v234, v250, v234
	v_sub_f32_e32 v235, v250, v235
	v_sub_f32_e32 v236, v250, v236
	v_sub_f32_e32 v237, v250, v237
	v_sub_f32_e32 v238, v250, v238
	v_sub_f32_e32 v239, v250, v239
	v_sub_f32_e32 v240, v250, v240
	s_waitcnt lgkmcnt(3)
	v_mfma_f32_32x32x16_bf16 v[132:147], v[152:155], v[180:183], v[132:147]
	ds_read_b128 v[152:155], v223 offset:34976
	v_sub_f32_e32 v241, v250, v241
	v_sub_f32_e32 v242, v250, v242
	v_sub_f32_e32 v243, v250, v243
	v_sub_f32_e32 v244, v250, v244
	v_sub_f32_e32 v245, v250, v245
	v_sub_f32_e32 v246, v250, v246
	v_sub_f32_e32 v247, v250, v247
	s_waitcnt lgkmcnt(3)
	v_mfma_f32_32x32x16_bf16 v[132:147], v[156:159], v[184:187], v[132:147]
	ds_read_b128 v[156:159], v223 offset:35008
	v_sub_f32_e32 v248, v250, v248
	v_sub_f32_e32 v249, v250, v249
	v_exp_f32_e32 v234, v234
	v_exp_f32_e32 v235, v235
	v_exp_f32_e32 v236, v236
	v_exp_f32_e32 v237, v237
	v_exp_f32_e32 v238, v238
	s_waitcnt lgkmcnt(3)
	v_mfma_f32_32x32x16_bf16 v[132:147], v[160:163], v[188:191], v[132:147]
	ds_read_b128 v[160:163], v223 offset:35040
	v_exp_f32_e32 v239, v239
	v_exp_f32_e32 v240, v240
	v_exp_f32_e32 v241, v241
	v_exp_f32_e32 v242, v242
	v_exp_f32_e32 v243, v243
	v_exp_f32_e32 v244, v244
	v_exp_f32_e32 v245, v245
	s_waitcnt lgkmcnt(3)
	v_mfma_f32_32x32x16_bf16 v[132:147], v[148:151], v[192:195], v[132:147]
	v_exp_f32_e32 v246, v246
	v_exp_f32_e32 v247, v247
	v_exp_f32_e32 v248, v248
	v_exp_f32_e32 v249, v249
	v_mul_f32_e32 v116, v116, v234
	v_mul_f32_e32 v117, v117, v235
	v_mul_f32_e32 v118, v118, v236
	s_waitcnt lgkmcnt(2)
	v_mfma_f32_32x32x16_bf16 v[132:147], v[152:155], v[196:199], v[132:147]
	v_mul_f32_e32 v119, v119, v237
	v_mul_f32_e32 v120, v120, v238
	v_mul_f32_e32 v121, v121, v239
	v_mul_f32_e32 v122, v122, v240
	v_mul_f32_e32 v123, v123, v241
	v_mul_f32_e32 v124, v124, v242
	v_mul_f32_e32 v125, v125, v243
	s_waitcnt lgkmcnt(1)
	v_mfma_f32_32x32x16_bf16 v[132:147], v[156:159], v[200:203], v[132:147]
	v_mul_f32_e32 v126, v126, v244
	v_mul_f32_e32 v127, v127, v245
	v_mul_f32_e32 v128, v128, v246
	v_mul_f32_e32 v129, v129, v247
	v_mul_f32_e32 v130, v130, v248
	v_mul_f32_e32 v131, v131, v249
	v_cvt_pk_bf16_f32 v116, v116, v117
	s_waitcnt lgkmcnt(0)
	v_mfma_f32_32x32x16_bf16 v[132:147], v[160:163], v[204:207], v[132:147]
	v_cvt_pk_bf16_f32 v117, v118, v119
	v_cvt_pk_bf16_f32 v118, v120, v121
	v_cvt_pk_bf16_f32 v119, v122, v123
	v_cvt_pk_bf16_f32 v120, v124, v125
	v_cvt_pk_bf16_f32 v121, v126, v127
	v_cvt_pk_bf16_f32 v122, v128, v129
	v_cvt_pk_bf16_f32 v123, v130, v131
	ds_read_b128 v[234:237], v224 offset:0
	ds_read_b128 v[238:241], v224 offset:32
	ds_read_b128 v[242:245], v224 offset:64
	ds_read_b128 v[246:249], v224 offset:96
	v_mfma_f32_32x32x16_bf16 v[76:91], v[36:39], v[116:119], v[76:91]
	v_mfma_f32_32x32x16_bf16 v[76:91], v[72:75], v[120:123], v[76:91]
	ds_read_b64_tr_b16 v[36:37], v225 offset:43008
	ds_read_b64_tr_b16 v[38:39], v225 offset:43520
	ds_read_b64_tr_b16 v[72:73], v225 offset:44032
	ds_read_b64_tr_b16 v[74:75], v225 offset:44544
	s_waitcnt lgkmcnt(4)
	ds_read_b128 v[148:151], v210 offset:8704
	ds_read_b128 v[152:155], v210 offset:8736
	ds_read_b128 v[156:159], v210 offset:8768
	ds_read_b128 v[160:163], v210 offset:8800
	s_waitcnt lgkmcnt(3)
	v_mfma_f32_32x32x16_bf16 v[92:107], v[148:151], v[176:179], 0
	ds_read_b128 v[148:151], v210 offset:8832
	v_sub_f32_e32 v234, v250, v234
	v_sub_f32_e32 v235, v250, v235
	v_sub_f32_e32 v236, v250, v236
	v_sub_f32_e32 v237, v250, v237
	v_sub_f32_e32 v238, v250, v238
	v_sub_f32_e32 v239, v250, v239
	v_sub_f32_e32 v240, v250, v240
	s_waitcnt lgkmcnt(3)
	v_mfma_f32_32x32x16_bf16 v[92:107], v[152:155], v[180:183], v[92:107]
	ds_read_b128 v[152:155], v210 offset:8864
	v_sub_f32_e32 v241, v250, v241
	v_sub_f32_e32 v242, v250, v242
	v_sub_f32_e32 v243, v250, v243
	v_sub_f32_e32 v244, v250, v244
	v_sub_f32_e32 v245, v250, v245
	v_sub_f32_e32 v246, v250, v246
	v_sub_f32_e32 v247, v250, v247
	s_waitcnt lgkmcnt(3)
	v_mfma_f32_32x32x16_bf16 v[92:107], v[156:159], v[184:187], v[92:107]
	ds_read_b128 v[156:159], v210 offset:8896
	v_sub_f32_e32 v248, v250, v248
	v_sub_f32_e32 v249, v250, v249
	v_exp_f32_e32 v234, v234
	v_exp_f32_e32 v235, v235
	v_exp_f32_e32 v236, v236
	v_exp_f32_e32 v237, v237
	v_exp_f32_e32 v238, v238
	s_waitcnt lgkmcnt(3)
	v_mfma_f32_32x32x16_bf16 v[92:107], v[160:163], v[188:191], v[92:107]
	ds_read_b128 v[160:163], v210 offset:8928
	v_exp_f32_e32 v239, v239
	v_exp_f32_e32 v240, v240
	v_exp_f32_e32 v241, v241
	v_exp_f32_e32 v242, v242
	v_exp_f32_e32 v243, v243
	v_exp_f32_e32 v244, v244
	v_exp_f32_e32 v245, v245
	s_waitcnt lgkmcnt(3)
	v_mfma_f32_32x32x16_bf16 v[92:107], v[148:151], v[192:195], v[92:107]
	v_exp_f32_e32 v246, v246
	v_exp_f32_e32 v247, v247
	v_exp_f32_e32 v248, v248
	v_exp_f32_e32 v249, v249
	v_mul_f32_e32 v132, v132, v234
	v_mul_f32_e32 v133, v133, v235
	v_mul_f32_e32 v134, v134, v236
	s_waitcnt lgkmcnt(2)
	v_mfma_f32_32x32x16_bf16 v[92:107], v[152:155], v[196:199], v[92:107]
	v_mul_f32_e32 v135, v135, v237
	v_mul_f32_e32 v136, v136, v238
	v_mul_f32_e32 v137, v137, v239
	v_mul_f32_e32 v138, v138, v240
	v_mul_f32_e32 v139, v139, v241
	v_mul_f32_e32 v140, v140, v242
	v_mul_f32_e32 v141, v141, v243
	s_waitcnt lgkmcnt(1)
	v_mfma_f32_32x32x16_bf16 v[92:107], v[156:159], v[200:203], v[92:107]
	v_mul_f32_e32 v142, v142, v244
	v_mul_f32_e32 v143, v143, v245
	v_mul_f32_e32 v144, v144, v246
	v_mul_f32_e32 v145, v145, v247
	v_mul_f32_e32 v146, v146, v248
	v_mul_f32_e32 v147, v147, v249
	v_cvt_pk_bf16_f32 v132, v132, v133
	s_waitcnt lgkmcnt(0)
	v_mfma_f32_32x32x16_bf16 v[92:107], v[160:163], v[204:207], v[92:107]
	v_cvt_pk_bf16_f32 v133, v134, v135
	v_cvt_pk_bf16_f32 v134, v136, v137
	v_cvt_pk_bf16_f32 v135, v138, v139
	v_cvt_pk_bf16_f32 v136, v140, v141
	v_cvt_pk_bf16_f32 v137, v142, v143
	v_cvt_pk_bf16_f32 v138, v144, v145
	v_cvt_pk_bf16_f32 v139, v146, v147
	v_mfma_f32_32x32x16_bf16 v[76:91], v[36:39], v[132:135], v[76:91]
	v_mfma_f32_32x32x16_bf16 v[76:91], v[72:75], v[136:139], v[76:91]
	s_branch .Lm_ydone_31

.Lm_ydone_31:
	s_waitcnt lgkmcnt(0)
	v_exp_f32_e32 v250, v250
	s_nop 7
	s_nop 3
	v_fma_f32 v76, v92, v250, v76
	v_fma_f32 v77, v93, v250, v77
	v_fma_f32 v78, v94, v250, v78
	v_fma_f32 v79, v95, v250, v79
	v_fma_f32 v80, v96, v250, v80
	v_fma_f32 v81, v97, v250, v81
	v_fma_f32 v82, v98, v250, v82
	v_fma_f32 v83, v99, v250, v83
	v_fma_f32 v84, v100, v250, v84
	v_fma_f32 v85, v101, v250, v85
	v_fma_f32 v86, v102, v250, v86
	v_fma_f32 v87, v103, v250, v87
	v_fma_f32 v88, v104, v250, v88
	v_fma_f32 v89, v105, v250, v89
	v_fma_f32 v90, v106, v250, v90
	v_fma_f32 v91, v107, v250, v91
	v_cvt_pk_bf16_f32 v148, v76, v77
	v_cvt_pk_bf16_f32 v149, v78, v79
	v_cvt_pk_bf16_f32 v150, v80, v81
	v_cvt_pk_bf16_f32 v151, v82, v83
	v_cvt_pk_bf16_f32 v152, v84, v85
	v_cvt_pk_bf16_f32 v153, v86, v87
	v_cvt_pk_bf16_f32 v154, v88, v89
	v_cvt_pk_bf16_f32 v155, v90, v91
	ds_write_b64 v168, v[148:149] offset:0
	ds_write_b64 v168, v[150:151] offset:16
	ds_write_b64 v168, v[152:153] offset:32
	ds_write_b64 v168, v[154:155] offset:48
	s_waitcnt lgkmcnt(0)
	ds_read_b128 v[156:159], v169
	ds_read_b128 v[160:163], v169 offset:1280
	s_waitcnt lgkmcnt(0)
	global_store_dwordx4 v170, v[156:159], s[44:45]
	global_store_dwordx4 v171, v[160:163], s[44:45]
	s_add_u32 s44, s44, s49
	s_addc_u32 s45, s45, s55
	s_waitcnt vmcnt(12)
	ds_write_b128 v166, v[4:7] offset:0
	ds_write_b128 v166, v[8:11] offset:272
	ds_write_b128 v166, v[12:15] offset:544
	ds_write_b128 v166, v[16:19] offset:816
	ds_write_b128 v166, v[20:23] offset:1088
	ds_write_b128 v166, v[24:27] offset:1360
	ds_write_b128 v166, v[28:31] offset:1632
	ds_write_b128 v166, v[32:35] offset:1904
	global_load_dwordx4 v[4:7], v164, s[38:39] offset:0
	global_load_dwordx4 v[8:11], v164, s[38:39] offset:512
	global_load_dwordx4 v[12:15], v164, s[38:39] offset:1024
	global_load_dwordx4 v[16:19], v164, s[38:39] offset:1536
	global_load_dwordx4 v[20:23], v164, s[38:39] offset:2048
	global_load_dwordx4 v[24:27], v164, s[38:39] offset:2560
	global_load_dwordx4 v[28:31], v164, s[38:39] offset:3072
	global_load_dwordx4 v[32:35], v164, s[38:39] offset:3584
	s_add_u32 s38, s38, s46
	s_addc_u32 s39, s39, s55
	s_branch .Lm_stepdone_24
.Lm_hi_23:
	v_add_u32_e32 v2, s14, v173
	ds_read_b32 v1, v2
	ds_read_b64_tr_b16 v[116:117], v198 offset:0
	ds_read_b64_tr_b16 v[118:119], v198 offset:1088
	ds_read_b64_tr_b16 v[120:121], v192 offset:43008
	ds_read_b64_tr_b16 v[122:123], v192 offset:43264
	ds_read_b64_tr_b16 v[124:125], v198 offset:4352
	ds_read_b64_tr_b16 v[126:127], v198 offset:5440
	ds_read_b64_tr_b16 v[128:129], v192 offset:44032
	ds_read_b64_tr_b16 v[130:131], v192 offset:44288
	ds_read_b64_tr_b16 v[132:133], v198 offset:8704
	ds_read_b64_tr_b16 v[134:135], v198 offset:9792
	ds_read_b64_tr_b16 v[136:137], v192 offset:45056
	ds_read_b64_tr_b16 v[138:139], v192 offset:45312
	s_waitcnt lgkmcnt(12)
	v_exp_f32_e32 v1, v1
	s_nop 0
	v_mul_f32_e32 v176, v176, v1
	v_mul_f32_e32 v177, v177, v1
	v_mul_f32_e32 v178, v178, v1
	v_mul_f32_e32 v179, v179, v1
	v_mul_f32_e32 v180, v180, v1
	v_mul_f32_e32 v181, v181, v1
	v_mul_f32_e32 v182, v182, v1
	v_mul_f32_e32 v183, v183, v1
	v_mul_f32_e32 v184, v184, v1
	v_mul_f32_e32 v185, v185, v1
	v_mul_f32_e32 v186, v186, v1
	v_mul_f32_e32 v187, v187, v1
	v_mul_f32_e32 v188, v188, v1
	v_mul_f32_e32 v189, v189, v1
	v_mul_f32_e32 v190, v190, v1
	v_mul_f32_e32 v191, v191, v1
	s_nop 1
	s_waitcnt lgkmcnt(8)
	v_mfma_f32_32x32x16_bf16 v[176:191], v[116:119], v[120:123], v[176:191]
	ds_read_b64_tr_b16 v[116:117], v198 offset:13056
	ds_read_b64_tr_b16 v[118:119], v198 offset:14144
	ds_read_b64_tr_b16 v[120:121], v192 offset:46080
	ds_read_b64_tr_b16 v[122:123], v192 offset:46336
	s_waitcnt lgkmcnt(8)
	v_mfma_f32_32x32x16_bf16 v[176:191], v[124:127], v[128:131], v[176:191]
	ds_read_b64_tr_b16 v[124:125], v198 offset:17408
	ds_read_b64_tr_b16 v[126:127], v198 offset:18496
	ds_read_b64_tr_b16 v[128:129], v192 offset:47104
	ds_read_b64_tr_b16 v[130:131], v192 offset:47360
	s_waitcnt lgkmcnt(8)
	v_mfma_f32_32x32x16_bf16 v[176:191], v[132:135], v[136:139], v[176:191]
	ds_read_b64_tr_b16 v[132:133], v198 offset:21760
	ds_read_b64_tr_b16 v[134:135], v198 offset:22848
	ds_read_b64_tr_b16 v[136:137], v192 offset:48128
	ds_read_b64_tr_b16 v[138:139], v192 offset:48384
	s_waitcnt lgkmcnt(8)
	v_mfma_f32_32x32x16_bf16 v[176:191], v[116:119], v[120:123], v[176:191]
	ds_read_b64_tr_b16 v[116:117], v198 offset:26112
	ds_read_b64_tr_b16 v[118:119], v198 offset:27200
	ds_read_b64_tr_b16 v[120:121], v192 offset:49152
	ds_read_b64_tr_b16 v[122:123], v192 offset:49408
	s_waitcnt lgkmcnt(8)
	v_mfma_f32_32x32x16_bf16 v[176:191], v[124:127], v[128:131], v[176:191]
	ds_read_b64_tr_b16 v[124:125], v198 offset:30464
	ds_read_b64_tr_b16 v[126:127], v198 offset:31552
	ds_read_b64_tr_b16 v[128:129], v192 offset:50176
	ds_read_b64_tr_b16 v[130:131], v192 offset:50432
	s_waitcnt lgkmcnt(8)
	v_mfma_f32_32x32x16_bf16 v[176:191], v[132:135], v[136:139], v[176:191]
	s_waitcnt lgkmcnt(4)
	v_mfma_f32_32x32x16_bf16 v[176:191], v[116:119], v[120:123], v[176:191]
	s_waitcnt lgkmcnt(0)
	v_mfma_f32_32x32x16_bf16 v[176:191], v[124:127], v[128:131], v[176:191]
	s_nop 7
	s_nop 3
	v_cvt_pk_bf16_f32 v140, v176, v177
	v_cvt_pk_bf16_f32 v141, v178, v179
	v_cvt_pk_bf16_f32 v142, v180, v181
	v_cvt_pk_bf16_f32 v143, v182, v183
	v_cvt_pk_bf16_f32 v144, v184, v185
	v_cvt_pk_bf16_f32 v145, v186, v187
	v_cvt_pk_bf16_f32 v146, v188, v189
	v_cvt_pk_bf16_f32 v147, v190, v191
	ds_write_b64 v194, v[140:141] offset:0
	ds_write_b64 v194, v[142:143] offset:16
	ds_write_b64 v194, v[144:145] offset:32
	ds_write_b64 v194, v[146:147] offset:48
	s_cmp_eq_u32 s3, s18
	s_cbranch_scc1 .Lm_w7_26
	s_waitcnt vmcnt(10)
	s_branch .Lm_wj_27

.Lm_wj_27:
	v_add_u32_e32 v154, s16, v172
	v_add_u32_e32 v155, s16, v173
	ds_read_b32 v116, v155
	ds_read_b32 v117, v154
	ds_read_b32 v118, v154 offset:512
	ds_read_b32 v152, v154 offset:256
	ds_read_b32 v153, v154 offset:768
	ds_write_b128 v170, v[4:7] offset:0
	ds_write_b128 v170, v[8:11] offset:272
	ds_write_b128 v170, v[12:15] offset:544
	ds_write_b128 v170, v[16:19] offset:816
	ds_write_b128 v170, v[20:23] offset:1088
	ds_write_b128 v170, v[24:27] offset:1360
	ds_write_b128 v170, v[28:31] offset:1632
	ds_write_b128 v170, v[32:35] offset:1904
	v_lshlrev_b32_e32 v120, 16, v36
	v_and_b32_e32 v121, 0xffff0000, v36
	v_lshlrev_b32_e32 v122, 16, v37
	v_and_b32_e32 v123, 0xffff0000, v37
	v_lshlrev_b32_e32 v124, 16, v38
	v_and_b32_e32 v125, 0xffff0000, v38
	v_lshlrev_b32_e32 v126, 16, v39
	v_and_b32_e32 v127, 0xffff0000, v39
	s_waitcnt lgkmcnt(8)
	v_sub_f32_e32 v119, v116, v117
	v_exp_f32_e32 v119, v119
	v_mul_f32_e32 v128, v118, v120
	v_mul_f32_e32 v129, v118, v121
	v_mul_f32_e32 v130, v118, v122
	v_mul_f32_e32 v131, v118, v123
	v_mul_f32_e32 v132, v118, v124
	v_mul_f32_e32 v133, v118, v125
	v_mul_f32_e32 v134, v118, v126
	v_mul_f32_e32 v135, v118, v127
	v_mul_f32_e32 v119, v118, v119
	v_cvt_pk_bf16_f32 v144, v128, v129
	v_cvt_pk_bf16_f32 v145, v130, v131
	v_cvt_pk_bf16_f32 v146, v132, v133
	v_cvt_pk_bf16_f32 v147, v134, v135
	v_mul_f32_e32 v136, v119, v120
	v_mul_f32_e32 v137, v119, v121
	v_mul_f32_e32 v138, v119, v122
	v_mul_f32_e32 v139, v119, v123
	v_mul_f32_e32 v140, v119, v124
	v_mul_f32_e32 v141, v119, v125
	v_mul_f32_e32 v142, v119, v126
	v_mul_f32_e32 v143, v119, v127
	v_cvt_pk_bf16_f32 v148, v136, v137
	v_cvt_pk_bf16_f32 v149, v138, v139
	v_cvt_pk_bf16_f32 v150, v140, v141
	v_cvt_pk_bf16_f32 v151, v142, v143
	ds_write_b128 v171, v[144:147] offset:0
	ds_write_b128 v197, v[148:151] offset:0
	v_lshlrev_b32_e32 v120, 16, v40
	v_and_b32_e32 v121, 0xffff0000, v40
	v_lshlrev_b32_e32 v122, 16, v41
	v_and_b32_e32 v123, 0xffff0000, v41
	v_lshlrev_b32_e32 v124, 16, v42
	v_and_b32_e32 v125, 0xffff0000, v42
	v_lshlrev_b32_e32 v126, 16, v43
	v_and_b32_e32 v127, 0xffff0000, v43
	v_sub_f32_e32 v119, v116, v152
	v_exp_f32_e32 v119, v119
	v_mul_f32_e32 v128, v153, v120
	v_mul_f32_e32 v129, v153, v121
	v_mul_f32_e32 v130, v153, v122
	v_mul_f32_e32 v131, v153, v123
	v_mul_f32_e32 v132, v153, v124
	v_mul_f32_e32 v133, v153, v125
	v_mul_f32_e32 v134, v153, v126
	v_mul_f32_e32 v135, v153, v127
	v_mul_f32_e32 v119, v153, v119
	v_cvt_pk_bf16_f32 v144, v128, v129
	v_cvt_pk_bf16_f32 v145, v130, v131
	v_cvt_pk_bf16_f32 v146, v132, v133
	v_cvt_pk_bf16_f32 v147, v134, v135
	v_mul_f32_e32 v136, v119, v120
	v_mul_f32_e32 v137, v119, v121
	v_mul_f32_e32 v138, v119, v122
	v_mul_f32_e32 v139, v119, v123
	v_mul_f32_e32 v140, v119, v124
	v_mul_f32_e32 v141, v119, v125
	v_mul_f32_e32 v142, v119, v126
	v_mul_f32_e32 v143, v119, v127
	v_cvt_pk_bf16_f32 v148, v136, v137
	v_cvt_pk_bf16_f32 v149, v138, v139
	v_cvt_pk_bf16_f32 v150, v140, v141
	v_cvt_pk_bf16_f32 v151, v142, v143
	ds_write_b128 v171, v[144:147] offset:4096
	ds_write_b128 v197, v[148:151] offset:4096
	global_load_dwordx4 v[4:7], v164, s[38:39] offset:0
	global_load_dwordx4 v[8:11], v164, s[38:39] offset:512
	global_load_dwordx4 v[12:15], v164, s[38:39] offset:1024
	global_load_dwordx4 v[16:19], v164, s[38:39] offset:1536
	global_load_dwordx4 v[20:23], v164, s[38:39] offset:2048
	global_load_dwordx4 v[24:27], v164, s[38:39] offset:2560
	global_load_dwordx4 v[28:31], v164, s[38:39] offset:3072
	global_load_dwordx4 v[32:35], v164, s[38:39] offset:3584
	global_load_dwordx4 v[36:39], v168, s[40:41]
	global_load_dwordx4 v[40:43], v169, s[40:41]
	s_add_u32 s38, s38, s46
	s_addc_u32 s39, s39, s55
	s_add_u32 s40, s40, s47
	s_addc_u32 s41, s41, s55
	s_cmp_eq_u32 s3, s18
	s_cbranch_scc0 .Lm_noscan_25
	s_waitcnt vmcnt(10)
	v_mul_f32_e32 v116, s62, v204
	v_mul_f32_e32 v117, s62, v205
	v_add_f32_e32 v118, v116, v117
	v_add_u32_e32 v124, s17, v196
	v_add_u32_e32 v125, s17, v173
	v_add_f32_dpp v118, v118, v118 row_shr:1 row_mask:0xf bank_mask:0xf bound_ctrl:0
	s_nop 1
	v_add_f32_dpp v118, v118, v118 row_shr:2 row_mask:0xf bank_mask:0xf bound_ctrl:0
	s_nop 1
	v_add_f32_dpp v118, v118, v118 row_shr:4 row_mask:0xf bank_mask:0xf bound_ctrl:0
	s_nop 1
	v_add_f32_dpp v118, v118, v118 row_shr:8 row_mask:0xf bank_mask:0xf bound_ctrl:0
	s_nop 1
	v_add_f32_dpp v118, v118, v118 row_bcast:15 row_mask:0xa bank_mask:0xf
	s_nop 1
	v_add_f32_dpp v118, v118, v118 row_bcast:31 row_mask:0xc bank_mask:0xf
	s_nop 1
	v_readlane_b32 s97, v118, 63
	v_sub_f32_e32 v122, v118, v117
	v_mov_b32_e32 v123, v118
	s_nop 1
	s_cmp_eq_u32 s51, 0
	s_cbranch_scc1 .Lm_scanf_32
	v_sub_f32_e32 v122, s97, v122
	v_sub_f32_e32 v123, s97, v123
	v_fma_f32 v122, v204, s62, v122
	v_fma_f32 v123, v205, s62, v123

.Lm_noscan_25:
.Lm_stepdone_24:
	s_waitcnt lgkmcnt(0)
	s_barrier
	s_mov_b32 s14, s16
	s_mov_b32 s16, s17
	s_add_u32 s17, s17, 1280
	s_cmpk_eq_u32 s17, 5120
	s_cselect_b32 s17, 0, s17
	s_add_u32 s50, s50, 1
	s_cmp_lt_u32 s50, 64
	s_cbranch_scc1 .Lm_loop
	s_waitcnt vmcnt(0)
	s_add_u32 s61, s61, s58
	s_cmpk_gt_i32 s61, 0xff
	s_cbranch_scc0 .Lm_item
	s_mov_b32 s77, 0x800000

	.amdhsa_kernel _Z8mega_fwd4Args
		.amdhsa_group_segment_fixed_size 163840
		.amdhsa_private_segment_fixed_size 0
		.amdhsa_kernarg_size 1984
		.amdhsa_user_sgpr_count 2
		.amdhsa_user_sgpr_dispatch_ptr 0
		.amdhsa_user_sgpr_queue_ptr 0
		.amdhsa_user_sgpr_kernarg_segment_ptr 1
		.amdhsa_user_sgpr_dispatch_id 0
		.amdhsa_user_sgpr_kernarg_preload_length 0
		.amdhsa_user_sgpr_kernarg_preload_offset 0
		.amdhsa_user_sgpr_private_segment_size 0
		.amdhsa_uses_dynamic_stack 0
		.amdhsa_enable_private_segment 0
		.amdhsa_system_sgpr_workgroup_id_x 1
		.amdhsa_system_sgpr_workgroup_id_y 0
		.amdhsa_system_sgpr_workgroup_id_z 0
		.amdhsa_system_sgpr_workgroup_info 0
		.amdhsa_system_vgpr_workitem_id 2
		.amdhsa_next_free_vgpr 256
		.amdhsa_next_free_sgpr 100
		.amdhsa_accum_offset 256
		.amdhsa_reserve_vcc 1
		.amdhsa_float_round_mode_32 0
		.amdhsa_float_round_mode_16_64 0
		.amdhsa_float_denorm_mode_32 3
		.amdhsa_float_denorm_mode_16_64 3
		.amdhsa_dx10_clamp 1
		.amdhsa_ieee_mode 1
		.amdhsa_fp16_overflow 0
		.amdhsa_tg_split 0
		.amdhsa_exception_fp_ieee_invalid_op 0
		.amdhsa_exception_fp_denorm_src 0
		.amdhsa_exception_fp_ieee_div_zero 0
		.amdhsa_exception_fp_ieee_overflow 0
		.amdhsa_exception_fp_ieee_underflow 0
		.amdhsa_exception_fp_ieee_inexact 0
		.amdhsa_exception_int_div_zero 0
	.end_amdhsa_kernel

amdhsa.kernels:
  - .agpr_count:     0
    .args:
      - .offset:         0
        .size:           1728
        .value_kind:     by_value
      - .offset:         1728
        .size:           4
        .value_kind:     hidden_block_count_x
      - .offset:         1732
        .size:           4
        .value_kind:     hidden_block_count_y
      - .offset:         1736
        .size:           4
        .value_kind:     hidden_block_count_z
      - .offset:         1740
        .size:           2
        .value_kind:     hidden_group_size_x
      - .offset:         1742
        .size:           2
        .value_kind:     hidden_group_size_y
      - .offset:         1744
        .size:           2
        .value_kind:     hidden_group_size_z
      - .offset:         1746
        .size:           2
        .value_kind:     hidden_remainder_x
      - .offset:         1748
        .size:           2
        .value_kind:     hidden_remainder_y
      - .offset:         1750
        .size:           2
        .value_kind:     hidden_remainder_z
      - .offset:         1768
        .size:           8
        .value_kind:     hidden_global_offset_x
      - .offset:         1776
        .size:           8
        .value_kind:     hidden_global_offset_y
      - .offset:         1784
        .size:           8
        .value_kind:     hidden_global_offset_z
      - .offset:         1792
        .size:           2
        .value_kind:     hidden_grid_dims
      - .offset:         1816
        .size:           8
        .value_kind:     hidden_multigrid_sync_arg
    .group_segment_fixed_size: 163840
    .kernarg_segment_align: 8
    .kernarg_segment_size: 1984
    .language:       OpenCL C
    .language_version:
      - 2
      - 0
    .max_flat_workgroup_size: 512
    .name:           _Z8mega_fwd4Args
    .private_segment_fixed_size: 0
    .sgpr_count:     106
    .sgpr_spill_count: 165
    .symbol:         _Z8mega_fwd4Args.kd
    .uniform_work_group_size: 1
    .uses_dynamic_stack: false
    .vgpr_count:     256
    .vgpr_spill_count: 0
    .wavefront_size: 64
